# GEMM main loops: loop counter / pointer increments and exit compare moved in front of the loop-back barrier (back-edge rotation, only the branch stays behind the barrier)
# speedup vs baseline: 1.0019x; 1.0019x over previous
.LBB0_206:
	s_add_u32 s1, s48, s50
	s_addc_u32 s10, s49, s51
	s_add_u32 s1, s1, 0x100
	s_addc_u32 s10, s10, 0
	s_add_u32 s14, s6, s50
	s_addc_u32 s11, s7, s51
	s_add_i32 s15, 0, 0x10000
	s_cmpk_eq_i32 s50, 0x700
	s_cselect_b32 s13, s43, s10
	s_cselect_b32 s12, s73, s1
	v_add_u32_e32 v152, s15, v164
	s_cselect_b32 s11, s75, s11
	s_cselect_b32 s10, s88, s14
	s_add_i32 s1, 0, 0x14000
	ds_read_b128 v[132:135], v152
	ds_read_b128 v[136:139], v152 offset:1024
	ds_read_b128 v[172:175], v152 offset:2048
	ds_read_b128 v[190:193], v152 offset:3072
	v_add_u32_e32 v152, s1, v164
	ds_read_b128 v[194:197], v152
	ds_read_b128 v[198:201], v152 offset:1024
	ds_read_b128 v[202:205], v152 offset:2048
	ds_read_b128 v[206:209], v152 offset:3072
	v_lshl_add_u64 v[152:153], v[162:163], 0, s[50:51]
	s_add_i32 m0, s52, 0xc000
	ds_read_b128 v[210:213], v167
	ds_read_b128 v[214:217], v167 offset:1024
	ds_read_b128 v[218:221], v167 offset:2048
	ds_read_b128 v[222:225], v167 offset:3072
	ds_read_b128 v[226:229], v167 offset:4096
	ds_read_b128 v[230:233], v167 offset:5120
	ds_read_b128 v[234:237], v167 offset:6144
	ds_read_b128 v[238:241], v167 offset:7168
	global_load_lds_dwordx4 v[152:153], off
	v_lshl_add_u64 v[152:153], v[160:161], 0, s[50:51]
	s_add_i32 m0, s52, 0xe000
	s_nop 0
	global_load_lds_dwordx4 v[152:153], off
	s_waitcnt vmcnt(8)
	s_waitcnt lgkmcnt(0)
	s_barrier
	s_waitcnt lgkmcnt(0)
	v_mfma_f32_16x16x32_bf16 v[128:131], v[132:135], v[210:213], v[128:131]
	v_mfma_f32_16x16x32_bf16 v[124:127], v[172:175], v[210:213], v[124:127]
	v_mfma_f32_16x16x32_bf16 v[112:115], v[132:135], v[218:221], v[112:115]
	v_mfma_f32_16x16x32_bf16 v[108:111], v[172:175], v[218:221], v[108:111]
	v_mfma_f32_16x16x32_bf16 v[96:99], v[132:135], v[226:229], v[96:99]
	v_mfma_f32_16x16x32_bf16 v[92:95], v[172:175], v[226:229], v[92:95]
	v_mfma_f32_16x16x32_bf16 v[80:83], v[132:135], v[234:237], v[80:83]
	v_mfma_f32_16x16x32_bf16 v[76:79], v[172:175], v[234:237], v[76:79]
	v_mfma_f32_16x16x32_bf16 v[128:131], v[136:139], v[214:217], v[128:131]
	v_mfma_f32_16x16x32_bf16 v[124:127], v[190:193], v[214:217], v[124:127]
	v_mfma_f32_16x16x32_bf16 v[112:115], v[136:139], v[222:225], v[112:115]
	v_mfma_f32_16x16x32_bf16 v[108:111], v[190:193], v[222:225], v[108:111]
	v_mfma_f32_16x16x32_bf16 v[96:99], v[136:139], v[230:233], v[96:99]
	v_mfma_f32_16x16x32_bf16 v[92:95], v[190:193], v[230:233], v[92:95]
	v_mfma_f32_16x16x32_bf16 v[80:83], v[136:139], v[238:241], v[80:83]
	v_mfma_f32_16x16x32_bf16 v[76:79], v[190:193], v[238:241], v[76:79]
	v_mfma_f32_16x16x32_bf16 v[120:123], v[194:197], v[210:213], v[120:123]
	v_mfma_f32_16x16x32_bf16 v[116:119], v[202:205], v[210:213], v[116:119]
	v_mfma_f32_16x16x32_bf16 v[104:107], v[194:197], v[218:221], v[104:107]
	v_mfma_f32_16x16x32_bf16 v[100:103], v[202:205], v[218:221], v[100:103]
	v_mfma_f32_16x16x32_bf16 v[88:91], v[194:197], v[226:229], v[88:91]
	v_mfma_f32_16x16x32_bf16 v[84:87], v[202:205], v[226:229], v[84:87]
	v_mfma_f32_16x16x32_bf16 v[72:75], v[194:197], v[234:237], v[72:75]
	v_mfma_f32_16x16x32_bf16 v[68:71], v[202:205], v[234:237], v[68:71]
	v_mfma_f32_16x16x32_bf16 v[120:123], v[198:201], v[214:217], v[120:123]
	v_mfma_f32_16x16x32_bf16 v[116:119], v[206:209], v[214:217], v[116:119]
	v_mfma_f32_16x16x32_bf16 v[104:107], v[198:201], v[222:225], v[104:107]
	v_mfma_f32_16x16x32_bf16 v[100:103], v[206:209], v[222:225], v[100:103]
	v_mfma_f32_16x16x32_bf16 v[88:91], v[198:201], v[230:233], v[88:91]
	v_mfma_f32_16x16x32_bf16 v[84:87], v[206:209], v[230:233], v[84:87]
	v_mfma_f32_16x16x32_bf16 v[72:75], v[198:201], v[238:241], v[72:75]
	v_mfma_f32_16x16x32_bf16 v[68:71], v[206:209], v[238:241], v[68:71]
	s_barrier
	s_add_i32 s14, s15, s19
	v_lshl_add_u64 v[152:153], s[10:11], 0, v[140:141]
	s_mov_b32 m0, s14
	ds_read_b128 v[210:213], v167 offset:16384
	ds_read_b128 v[214:217], v167 offset:17408
	ds_read_b128 v[218:221], v167 offset:18432
	ds_read_b128 v[222:225], v167 offset:19456
	ds_read_b128 v[226:229], v167 offset:20480
	ds_read_b128 v[230:233], v167 offset:21504
	ds_read_b128 v[234:237], v167 offset:22528
	ds_read_b128 v[238:241], v167 offset:23552
	global_load_lds_dwordx4 v[152:153], off
	s_add_i32 m0, s14, 0x2000
	s_add_u32 s14, s10, 0x40000
	v_lshl_add_u64 v[242:243], s[10:11], 0, v[144:145]
	s_addc_u32 s15, s11, 0
	s_add_i32 s1, s1, s19
	global_load_lds_dwordx4 v[242:243], off
	v_lshl_add_u64 v[244:245], s[14:15], 0, v[140:141]
	s_mov_b32 m0, s1
	v_lshl_add_u64 v[246:247], s[12:13], 0, v[142:143]
	global_load_lds_dwordx4 v[244:245], off
	v_lshl_add_u64 v[244:245], s[14:15], 0, v[144:145]
	s_add_i32 m0, s1, 0x2000
	s_nop 0
	global_load_lds_dwordx4 v[244:245], off
	v_lshl_add_u64 v[244:245], s[12:13], 0, v[0:1]
	s_mov_b32 m0, s52
	s_nop 0
	global_load_lds_dwordx4 v[244:245], off
	s_mov_b32 m0, s53
	s_nop 0
	global_load_lds_dwordx4 v[246:247], off
	s_waitcnt vmcnt(8)
	s_waitcnt lgkmcnt(0)
	s_barrier
	s_waitcnt lgkmcnt(0)
	v_mfma_f32_16x16x32_bf16 v[64:67], v[132:135], v[210:213], v[64:67]
	v_mfma_f32_16x16x32_bf16 v[60:63], v[172:175], v[210:213], v[60:63]
	v_mfma_f32_16x16x32_bf16 v[48:51], v[132:135], v[218:221], v[48:51]
	v_mfma_f32_16x16x32_bf16 v[44:47], v[172:175], v[218:221], v[44:47]
	v_mfma_f32_16x16x32_bf16 v[32:35], v[132:135], v[226:229], v[32:35]
	v_mfma_f32_16x16x32_bf16 v[28:31], v[172:175], v[226:229], v[28:31]
	v_mfma_f32_16x16x32_bf16 v[16:19], v[132:135], v[234:237], v[16:19]
	v_mfma_f32_16x16x32_bf16 v[12:15], v[172:175], v[234:237], v[12:15]
	v_mfma_f32_16x16x32_bf16 v[64:67], v[136:139], v[214:217], v[64:67]
	v_mfma_f32_16x16x32_bf16 v[60:63], v[190:193], v[214:217], v[60:63]
	v_mfma_f32_16x16x32_bf16 v[48:51], v[136:139], v[222:225], v[48:51]
	v_mfma_f32_16x16x32_bf16 v[44:47], v[190:193], v[222:225], v[44:47]
	v_mfma_f32_16x16x32_bf16 v[32:35], v[136:139], v[230:233], v[32:35]
	v_mfma_f32_16x16x32_bf16 v[28:31], v[190:193], v[230:233], v[28:31]
	v_mfma_f32_16x16x32_bf16 v[16:19], v[136:139], v[238:241], v[16:19]
	v_mfma_f32_16x16x32_bf16 v[12:15], v[190:193], v[238:241], v[12:15]
	v_mfma_f32_16x16x32_bf16 v[56:59], v[194:197], v[210:213], v[56:59]
	v_mfma_f32_16x16x32_bf16 v[52:55], v[202:205], v[210:213], v[52:55]
	v_mfma_f32_16x16x32_bf16 v[40:43], v[194:197], v[218:221], v[40:43]
	v_mfma_f32_16x16x32_bf16 v[36:39], v[202:205], v[218:221], v[36:39]
	v_mfma_f32_16x16x32_bf16 v[24:27], v[194:197], v[226:229], v[24:27]
	v_mfma_f32_16x16x32_bf16 v[20:23], v[202:205], v[226:229], v[20:23]
	v_mfma_f32_16x16x32_bf16 v[8:11], v[194:197], v[234:237], v[8:11]
	v_mfma_f32_16x16x32_bf16 v[4:7], v[202:205], v[234:237], v[4:7]
	v_mfma_f32_16x16x32_bf16 v[56:59], v[198:201], v[214:217], v[56:59]
	v_mfma_f32_16x16x32_bf16 v[52:55], v[206:209], v[214:217], v[52:55]
	v_mfma_f32_16x16x32_bf16 v[40:43], v[198:201], v[222:225], v[40:43]
	v_mfma_f32_16x16x32_bf16 v[36:39], v[206:209], v[222:225], v[36:39]
	v_mfma_f32_16x16x32_bf16 v[24:27], v[198:201], v[230:233], v[24:27]
	v_mfma_f32_16x16x32_bf16 v[20:23], v[206:209], v[230:233], v[20:23]
	v_mfma_f32_16x16x32_bf16 v[8:11], v[198:201], v[238:241], v[8:11]
	v_mfma_f32_16x16x32_bf16 v[4:7], v[206:209], v[238:241], v[4:7]
	s_barrier
	s_add_i32 s1, 0, 0x18000
	s_add_i32 s14, 0, 0x1c000
	v_add_u32_e32 v190, s1, v164
	v_add_u32_e32 v206, s14, v164
	ds_read_b128 v[132:135], v190
	ds_read_b128 v[136:139], v190 offset:1024
	ds_read_b128 v[172:175], v190 offset:2048
	ds_read_b128 v[190:193], v190 offset:3072
	ds_read_b128 v[194:197], v206
	ds_read_b128 v[198:201], v206 offset:1024
	ds_read_b128 v[202:205], v206 offset:2048
	ds_read_b128 v[206:209], v206 offset:3072
	s_add_u32 s12, s12, 0x40000
	s_addc_u32 s13, s13, 0
	s_mov_b32 m0, s54
	v_lshl_add_u64 v[248:249], s[12:13], 0, v[0:1]
	ds_read_b128 v[210:213], v167 offset:32768
	ds_read_b128 v[214:217], v167 offset:33792
	ds_read_b128 v[218:221], v167 offset:34816
	ds_read_b128 v[222:225], v167 offset:35840
	ds_read_b128 v[226:229], v167 offset:36864
	ds_read_b128 v[230:233], v167 offset:37888
	ds_read_b128 v[234:237], v167 offset:38912
	ds_read_b128 v[238:241], v167 offset:39936
	global_load_lds_dwordx4 v[248:249], off
	v_lshl_add_u64 v[248:249], s[12:13], 0, v[142:143]
	s_mov_b32 m0, s55
	s_nop 0
	global_load_lds_dwordx4 v[248:249], off
	s_waitcnt vmcnt(8)
	s_waitcnt lgkmcnt(0)
	s_barrier
	s_waitcnt lgkmcnt(0)
	v_mfma_f32_16x16x32_bf16 v[128:131], v[132:135], v[210:213], v[128:131]
	v_mfma_f32_16x16x32_bf16 v[124:127], v[172:175], v[210:213], v[124:127]
	v_mfma_f32_16x16x32_bf16 v[112:115], v[132:135], v[218:221], v[112:115]
	v_mfma_f32_16x16x32_bf16 v[108:111], v[172:175], v[218:221], v[108:111]
	v_mfma_f32_16x16x32_bf16 v[96:99], v[132:135], v[226:229], v[96:99]
	v_mfma_f32_16x16x32_bf16 v[92:95], v[172:175], v[226:229], v[92:95]
	v_mfma_f32_16x16x32_bf16 v[80:83], v[132:135], v[234:237], v[80:83]
	v_mfma_f32_16x16x32_bf16 v[76:79], v[172:175], v[234:237], v[76:79]
	v_mfma_f32_16x16x32_bf16 v[128:131], v[136:139], v[214:217], v[128:131]
	v_mfma_f32_16x16x32_bf16 v[124:127], v[190:193], v[214:217], v[124:127]
	v_mfma_f32_16x16x32_bf16 v[112:115], v[136:139], v[222:225], v[112:115]
	v_mfma_f32_16x16x32_bf16 v[108:111], v[190:193], v[222:225], v[108:111]
	v_mfma_f32_16x16x32_bf16 v[96:99], v[136:139], v[230:233], v[96:99]
	v_mfma_f32_16x16x32_bf16 v[92:95], v[190:193], v[230:233], v[92:95]
	v_mfma_f32_16x16x32_bf16 v[80:83], v[136:139], v[238:241], v[80:83]
	v_mfma_f32_16x16x32_bf16 v[76:79], v[190:193], v[238:241], v[76:79]
	v_mfma_f32_16x16x32_bf16 v[120:123], v[194:197], v[210:213], v[120:123]
	v_mfma_f32_16x16x32_bf16 v[116:119], v[202:205], v[210:213], v[116:119]
	v_mfma_f32_16x16x32_bf16 v[104:107], v[194:197], v[218:221], v[104:107]
	v_mfma_f32_16x16x32_bf16 v[100:103], v[202:205], v[218:221], v[100:103]
	v_mfma_f32_16x16x32_bf16 v[88:91], v[194:197], v[226:229], v[88:91]
	v_mfma_f32_16x16x32_bf16 v[84:87], v[202:205], v[226:229], v[84:87]
	v_mfma_f32_16x16x32_bf16 v[72:75], v[194:197], v[234:237], v[72:75]
	v_mfma_f32_16x16x32_bf16 v[68:71], v[202:205], v[234:237], v[68:71]
	v_mfma_f32_16x16x32_bf16 v[120:123], v[198:201], v[214:217], v[120:123]
	v_mfma_f32_16x16x32_bf16 v[116:119], v[206:209], v[214:217], v[116:119]
	v_mfma_f32_16x16x32_bf16 v[104:107], v[198:201], v[222:225], v[104:107]
	v_mfma_f32_16x16x32_bf16 v[100:103], v[206:209], v[222:225], v[100:103]
	v_mfma_f32_16x16x32_bf16 v[88:91], v[198:201], v[230:233], v[88:91]
	v_mfma_f32_16x16x32_bf16 v[84:87], v[206:209], v[230:233], v[84:87]
	v_mfma_f32_16x16x32_bf16 v[72:75], v[198:201], v[238:241], v[72:75]
	v_mfma_f32_16x16x32_bf16 v[68:71], v[206:209], v[238:241], v[68:71]
	s_barrier
	s_add_i32 s1, s1, s19
	v_lshl_add_u64 v[152:153], v[152:153], 0, s[84:85]
	s_mov_b32 m0, s1
	ds_read_b128 v[210:213], v167 offset:49152
	ds_read_b128 v[214:217], v167 offset:50176
	ds_read_b128 v[218:221], v167 offset:51200
	ds_read_b128 v[222:225], v167 offset:52224
	ds_read_b128 v[226:229], v167 offset:53248
	ds_read_b128 v[230:233], v167 offset:54272
	ds_read_b128 v[234:237], v167 offset:55296
	ds_read_b128 v[238:241], v167 offset:56320
	global_load_lds_dwordx4 v[152:153], off
	s_add_i32 m0, s1, 0x2000
	s_add_u32 s10, s10, 0x40080
	v_lshl_add_u64 v[152:153], v[242:243], 0, s[84:85]
	s_addc_u32 s11, s11, 0
	s_add_i32 s1, s14, s19
	global_load_lds_dwordx4 v[152:153], off
	v_lshl_add_u64 v[152:153], s[10:11], 0, v[140:141]
	s_mov_b32 m0, s1
	s_nop 0
	global_load_lds_dwordx4 v[152:153], off
	v_lshl_add_u64 v[152:153], s[10:11], 0, v[144:145]
	s_add_i32 m0, s1, 0x2000
	s_nop 0
	global_load_lds_dwordx4 v[152:153], off
	v_lshl_add_u64 v[152:153], v[244:245], 0, s[84:85]
	s_mov_b32 m0, s58
	s_nop 0
	global_load_lds_dwordx4 v[152:153], off
	v_lshl_add_u64 v[152:153], v[246:247], 0, s[84:85]
	s_mov_b32 m0, s59
	s_nop 0
	global_load_lds_dwordx4 v[152:153], off
	s_waitcnt vmcnt(8)
	s_waitcnt lgkmcnt(0)
	s_barrier
	s_waitcnt lgkmcnt(0)
	v_mfma_f32_16x16x32_bf16 v[64:67], v[132:135], v[210:213], v[64:67]
	v_mfma_f32_16x16x32_bf16 v[60:63], v[172:175], v[210:213], v[60:63]
	v_mfma_f32_16x16x32_bf16 v[48:51], v[132:135], v[218:221], v[48:51]
	v_mfma_f32_16x16x32_bf16 v[44:47], v[172:175], v[218:221], v[44:47]
	v_mfma_f32_16x16x32_bf16 v[32:35], v[132:135], v[226:229], v[32:35]
	v_mfma_f32_16x16x32_bf16 v[28:31], v[172:175], v[226:229], v[28:31]
	v_mfma_f32_16x16x32_bf16 v[16:19], v[132:135], v[234:237], v[16:19]
	v_mfma_f32_16x16x32_bf16 v[12:15], v[172:175], v[234:237], v[12:15]
	v_mfma_f32_16x16x32_bf16 v[64:67], v[136:139], v[214:217], v[64:67]
	v_mfma_f32_16x16x32_bf16 v[60:63], v[190:193], v[214:217], v[60:63]
	v_mfma_f32_16x16x32_bf16 v[48:51], v[136:139], v[222:225], v[48:51]
	v_mfma_f32_16x16x32_bf16 v[44:47], v[190:193], v[222:225], v[44:47]
	v_mfma_f32_16x16x32_bf16 v[32:35], v[136:139], v[230:233], v[32:35]
	v_mfma_f32_16x16x32_bf16 v[28:31], v[190:193], v[230:233], v[28:31]
	v_mfma_f32_16x16x32_bf16 v[16:19], v[136:139], v[238:241], v[16:19]
	v_mfma_f32_16x16x32_bf16 v[12:15], v[190:193], v[238:241], v[12:15]
	v_mfma_f32_16x16x32_bf16 v[56:59], v[194:197], v[210:213], v[56:59]
	v_mfma_f32_16x16x32_bf16 v[52:55], v[202:205], v[210:213], v[52:55]
	v_mfma_f32_16x16x32_bf16 v[40:43], v[194:197], v[218:221], v[40:43]
	v_mfma_f32_16x16x32_bf16 v[36:39], v[202:205], v[218:221], v[36:39]
	v_mfma_f32_16x16x32_bf16 v[24:27], v[194:197], v[226:229], v[24:27]
	v_mfma_f32_16x16x32_bf16 v[20:23], v[202:205], v[226:229], v[20:23]
	v_mfma_f32_16x16x32_bf16 v[8:11], v[194:197], v[234:237], v[8:11]
	v_mfma_f32_16x16x32_bf16 v[4:7], v[202:205], v[234:237], v[4:7]
	v_mfma_f32_16x16x32_bf16 v[56:59], v[198:201], v[214:217], v[56:59]
	v_mfma_f32_16x16x32_bf16 v[52:55], v[206:209], v[214:217], v[52:55]
	v_mfma_f32_16x16x32_bf16 v[40:43], v[198:201], v[222:225], v[40:43]
	v_mfma_f32_16x16x32_bf16 v[36:39], v[206:209], v[222:225], v[36:39]
	v_mfma_f32_16x16x32_bf16 v[24:27], v[198:201], v[230:233], v[24:27]
	v_mfma_f32_16x16x32_bf16 v[20:23], v[206:209], v[230:233], v[20:23]
	v_mfma_f32_16x16x32_bf16 v[8:11], v[198:201], v[238:241], v[8:11]
	v_mfma_f32_16x16x32_bf16 v[4:7], v[206:209], v[238:241], v[4:7]
	s_add_u32 s50, s50, 0x100
	s_addc_u32 s51, s51, 0
	s_cmp_gt_u32 s0, 13
	s_barrier
	s_cbranch_scc1 .LBB0_215

.Lsp_done_1:
.LBB0_437:
	s_add_u32 s14, s12, 0xfffc0080
	s_addc_u32 s15, s13, -1
	s_add_i32 s28, 0, 0x10000
	s_cmp_eq_u32 s27, 12
	s_cselect_b32 s17, s3, s15
	s_cselect_b32 s16, s11, s14
	v_add_u32_e32 v152, s28, v190
	s_cselect_b32 s15, s9, s24
	s_cselect_b32 s14, s22, s23
	s_add_i32 s31, 0, 0x14000
	ds_read_b128 v[132:135], v152
	ds_read_b128 v[136:139], v152 offset:1024
	ds_read_b128 v[160:163], v152 offset:2048
	ds_read_b128 v[164:167], v152 offset:3072
	v_add_u32_e32 v152, s31, v190
	ds_read_b128 v[168:171], v152
	ds_read_b128 v[172:175], v152 offset:1024
	ds_read_b128 v[196:199], v152 offset:2048
	ds_read_b128 v[200:203], v152 offset:3072
	v_lshl_add_u64 v[152:153], s[12:13], 0, v[158:159]
	s_add_i32 m0, s51, 0xc000
	ds_read_b128 v[204:207], v194
	ds_read_b128 v[208:211], v194 offset:1024
	ds_read_b128 v[212:215], v194 offset:2048
	ds_read_b128 v[216:219], v194 offset:3072
	ds_read_b128 v[220:223], v194 offset:4096
	ds_read_b128 v[224:227], v194 offset:5120
	ds_read_b128 v[228:231], v194 offset:6144
	ds_read_b128 v[232:235], v194 offset:7168
	global_load_lds_dwordx4 v[152:153], off
	v_lshl_add_u64 v[152:153], s[12:13], 0, v[146:147]
	s_add_i32 m0, s51, 0xe000
	s_nop 0
	global_load_lds_dwordx4 v[152:153], off
	s_waitcnt vmcnt(8)
	s_waitcnt lgkmcnt(0)
	s_barrier
	s_waitcnt lgkmcnt(0)
	v_mfma_f32_16x16x32_bf16 v[128:131], v[132:135], v[204:207], v[128:131]
	v_mfma_f32_16x16x32_bf16 v[124:127], v[160:163], v[204:207], v[124:127]
	v_mfma_f32_16x16x32_bf16 v[112:115], v[132:135], v[212:215], v[112:115]
	v_mfma_f32_16x16x32_bf16 v[108:111], v[160:163], v[212:215], v[108:111]
	v_mfma_f32_16x16x32_bf16 v[96:99], v[132:135], v[220:223], v[96:99]
	v_mfma_f32_16x16x32_bf16 v[92:95], v[160:163], v[220:223], v[92:95]
	v_mfma_f32_16x16x32_bf16 v[80:83], v[132:135], v[228:231], v[80:83]
	v_mfma_f32_16x16x32_bf16 v[76:79], v[160:163], v[228:231], v[76:79]
	v_mfma_f32_16x16x32_bf16 v[128:131], v[136:139], v[208:211], v[128:131]
	v_mfma_f32_16x16x32_bf16 v[124:127], v[164:167], v[208:211], v[124:127]
	v_mfma_f32_16x16x32_bf16 v[112:115], v[136:139], v[216:219], v[112:115]
	v_mfma_f32_16x16x32_bf16 v[108:111], v[164:167], v[216:219], v[108:111]
	v_mfma_f32_16x16x32_bf16 v[96:99], v[136:139], v[224:227], v[96:99]
	v_mfma_f32_16x16x32_bf16 v[92:95], v[164:167], v[224:227], v[92:95]
	v_mfma_f32_16x16x32_bf16 v[80:83], v[136:139], v[232:235], v[80:83]
	v_mfma_f32_16x16x32_bf16 v[76:79], v[164:167], v[232:235], v[76:79]
	v_mfma_f32_16x16x32_bf16 v[120:123], v[168:171], v[204:207], v[120:123]
	v_mfma_f32_16x16x32_bf16 v[116:119], v[196:199], v[204:207], v[116:119]
	v_mfma_f32_16x16x32_bf16 v[104:107], v[168:171], v[212:215], v[104:107]
	v_mfma_f32_16x16x32_bf16 v[100:103], v[196:199], v[212:215], v[100:103]
	v_mfma_f32_16x16x32_bf16 v[88:91], v[168:171], v[220:223], v[88:91]
	v_mfma_f32_16x16x32_bf16 v[84:87], v[196:199], v[220:223], v[84:87]
	v_mfma_f32_16x16x32_bf16 v[72:75], v[168:171], v[228:231], v[72:75]
	v_mfma_f32_16x16x32_bf16 v[68:71], v[196:199], v[228:231], v[68:71]
	v_mfma_f32_16x16x32_bf16 v[120:123], v[172:175], v[208:211], v[120:123]
	v_mfma_f32_16x16x32_bf16 v[116:119], v[200:203], v[208:211], v[116:119]
	v_mfma_f32_16x16x32_bf16 v[104:107], v[172:175], v[216:219], v[104:107]
	v_mfma_f32_16x16x32_bf16 v[100:103], v[200:203], v[216:219], v[100:103]
	v_mfma_f32_16x16x32_bf16 v[88:91], v[172:175], v[224:227], v[88:91]
	v_mfma_f32_16x16x32_bf16 v[84:87], v[200:203], v[224:227], v[84:87]
	v_mfma_f32_16x16x32_bf16 v[72:75], v[172:175], v[232:235], v[72:75]
	v_mfma_f32_16x16x32_bf16 v[68:71], v[200:203], v[232:235], v[68:71]
	s_barrier
	s_add_i32 s28, s28, s58
	v_lshl_add_u64 v[152:153], s[14:15], 0, v[140:141]
	s_mov_b32 m0, s28
	ds_read_b128 v[204:207], v194 offset:16384
	ds_read_b128 v[208:211], v194 offset:17408
	ds_read_b128 v[212:215], v194 offset:18432
	ds_read_b128 v[216:219], v194 offset:19456
	ds_read_b128 v[220:223], v194 offset:20480
	ds_read_b128 v[224:227], v194 offset:21504
	ds_read_b128 v[228:231], v194 offset:22528
	ds_read_b128 v[232:235], v194 offset:23552
	global_load_lds_dwordx4 v[152:153], off
	s_add_i32 m0, s28, 0x2000
	s_add_u32 s36, s14, 0x40000
	v_lshl_add_u64 v[236:237], s[14:15], 0, v[144:145]
	s_addc_u32 s37, s15, 0
	s_add_i32 s28, s31, s58
	global_load_lds_dwordx4 v[236:237], off
	v_lshl_add_u64 v[238:239], s[36:37], 0, v[140:141]
	s_mov_b32 m0, s28
	v_lshl_add_u64 v[240:241], s[16:17], 0, v[142:143]
	global_load_lds_dwordx4 v[238:239], off
	v_lshl_add_u64 v[238:239], s[36:37], 0, v[144:145]
	s_add_i32 m0, s28, 0x2000
	s_nop 0
	global_load_lds_dwordx4 v[238:239], off
	v_lshl_add_u64 v[238:239], s[16:17], 0, v[0:1]
	s_mov_b32 m0, s51
	s_nop 0
	global_load_lds_dwordx4 v[238:239], off
	s_mov_b32 m0, s59
	s_nop 0
	global_load_lds_dwordx4 v[240:241], off
	s_waitcnt vmcnt(8)
	s_waitcnt lgkmcnt(0)
	s_barrier
	s_waitcnt lgkmcnt(0)
	v_mfma_f32_16x16x32_bf16 v[64:67], v[132:135], v[204:207], v[64:67]
	v_mfma_f32_16x16x32_bf16 v[60:63], v[160:163], v[204:207], v[60:63]
	v_mfma_f32_16x16x32_bf16 v[48:51], v[132:135], v[212:215], v[48:51]
	v_mfma_f32_16x16x32_bf16 v[44:47], v[160:163], v[212:215], v[44:47]
	v_mfma_f32_16x16x32_bf16 v[32:35], v[132:135], v[220:223], v[32:35]
	v_mfma_f32_16x16x32_bf16 v[28:31], v[160:163], v[220:223], v[28:31]
	v_mfma_f32_16x16x32_bf16 v[16:19], v[132:135], v[228:231], v[16:19]
	v_mfma_f32_16x16x32_bf16 v[12:15], v[160:163], v[228:231], v[12:15]
	v_mfma_f32_16x16x32_bf16 v[64:67], v[136:139], v[208:211], v[64:67]
	v_mfma_f32_16x16x32_bf16 v[60:63], v[164:167], v[208:211], v[60:63]
	v_mfma_f32_16x16x32_bf16 v[48:51], v[136:139], v[216:219], v[48:51]
	v_mfma_f32_16x16x32_bf16 v[44:47], v[164:167], v[216:219], v[44:47]
	v_mfma_f32_16x16x32_bf16 v[32:35], v[136:139], v[224:227], v[32:35]
	v_mfma_f32_16x16x32_bf16 v[28:31], v[164:167], v[224:227], v[28:31]
	v_mfma_f32_16x16x32_bf16 v[16:19], v[136:139], v[232:235], v[16:19]
	v_mfma_f32_16x16x32_bf16 v[12:15], v[164:167], v[232:235], v[12:15]
	v_mfma_f32_16x16x32_bf16 v[56:59], v[168:171], v[204:207], v[56:59]
	v_mfma_f32_16x16x32_bf16 v[52:55], v[196:199], v[204:207], v[52:55]
	v_mfma_f32_16x16x32_bf16 v[40:43], v[168:171], v[212:215], v[40:43]
	v_mfma_f32_16x16x32_bf16 v[36:39], v[196:199], v[212:215], v[36:39]
	v_mfma_f32_16x16x32_bf16 v[24:27], v[168:171], v[220:223], v[24:27]
	v_mfma_f32_16x16x32_bf16 v[20:23], v[196:199], v[220:223], v[20:23]
	v_mfma_f32_16x16x32_bf16 v[8:11], v[168:171], v[228:231], v[8:11]
	v_mfma_f32_16x16x32_bf16 v[4:7], v[196:199], v[228:231], v[4:7]
	v_mfma_f32_16x16x32_bf16 v[56:59], v[172:175], v[208:211], v[56:59]
	v_mfma_f32_16x16x32_bf16 v[52:55], v[200:203], v[208:211], v[52:55]
	v_mfma_f32_16x16x32_bf16 v[40:43], v[172:175], v[216:219], v[40:43]
	v_mfma_f32_16x16x32_bf16 v[36:39], v[200:203], v[216:219], v[36:39]
	v_mfma_f32_16x16x32_bf16 v[24:27], v[172:175], v[224:227], v[24:27]
	v_mfma_f32_16x16x32_bf16 v[20:23], v[200:203], v[224:227], v[20:23]
	v_mfma_f32_16x16x32_bf16 v[8:11], v[172:175], v[232:235], v[8:11]
	v_mfma_f32_16x16x32_bf16 v[4:7], v[200:203], v[232:235], v[4:7]
	s_barrier
	s_add_i32 s28, 0, 0x18000
	s_add_i32 s31, 0, 0x1c000
	v_add_u32_e32 v164, s28, v190
	v_add_u32_e32 v195, s31, v190
	ds_read_b128 v[132:135], v164
	ds_read_b128 v[136:139], v164 offset:1024
	ds_read_b128 v[160:163], v164 offset:2048
	ds_read_b128 v[164:167], v164 offset:3072
	ds_read_b128 v[168:171], v195
	ds_read_b128 v[172:175], v195 offset:1024
	ds_read_b128 v[196:199], v195 offset:2048
	ds_read_b128 v[200:203], v195 offset:3072
	s_add_u32 s16, s16, 0x40000
	s_addc_u32 s17, s17, 0
	s_mov_b32 m0, s52
	v_lshl_add_u64 v[242:243], s[16:17], 0, v[0:1]
	ds_read_b128 v[204:207], v194 offset:32768
	ds_read_b128 v[208:211], v194 offset:33792
	ds_read_b128 v[212:215], v194 offset:34816
	ds_read_b128 v[216:219], v194 offset:35840
	ds_read_b128 v[220:223], v194 offset:36864
	ds_read_b128 v[224:227], v194 offset:37888
	ds_read_b128 v[228:231], v194 offset:38912
	ds_read_b128 v[232:235], v194 offset:39936
	global_load_lds_dwordx4 v[242:243], off
	v_lshl_add_u64 v[242:243], s[16:17], 0, v[142:143]
	s_mov_b32 m0, s71
	s_nop 0
	global_load_lds_dwordx4 v[242:243], off
	s_waitcnt vmcnt(8)
	s_waitcnt lgkmcnt(0)
	s_barrier
	s_waitcnt lgkmcnt(0)
	v_mfma_f32_16x16x32_bf16 v[128:131], v[132:135], v[204:207], v[128:131]
	v_mfma_f32_16x16x32_bf16 v[124:127], v[160:163], v[204:207], v[124:127]
	v_mfma_f32_16x16x32_bf16 v[112:115], v[132:135], v[212:215], v[112:115]
	v_mfma_f32_16x16x32_bf16 v[108:111], v[160:163], v[212:215], v[108:111]
	v_mfma_f32_16x16x32_bf16 v[96:99], v[132:135], v[220:223], v[96:99]
	v_mfma_f32_16x16x32_bf16 v[92:95], v[160:163], v[220:223], v[92:95]
	v_mfma_f32_16x16x32_bf16 v[80:83], v[132:135], v[228:231], v[80:83]
	v_mfma_f32_16x16x32_bf16 v[76:79], v[160:163], v[228:231], v[76:79]
	v_mfma_f32_16x16x32_bf16 v[128:131], v[136:139], v[208:211], v[128:131]
	v_mfma_f32_16x16x32_bf16 v[124:127], v[164:167], v[208:211], v[124:127]
	v_mfma_f32_16x16x32_bf16 v[112:115], v[136:139], v[216:219], v[112:115]
	v_mfma_f32_16x16x32_bf16 v[108:111], v[164:167], v[216:219], v[108:111]
	v_mfma_f32_16x16x32_bf16 v[96:99], v[136:139], v[224:227], v[96:99]
	v_mfma_f32_16x16x32_bf16 v[92:95], v[164:167], v[224:227], v[92:95]
	v_mfma_f32_16x16x32_bf16 v[80:83], v[136:139], v[232:235], v[80:83]
	v_mfma_f32_16x16x32_bf16 v[76:79], v[164:167], v[232:235], v[76:79]
	v_mfma_f32_16x16x32_bf16 v[120:123], v[168:171], v[204:207], v[120:123]
	v_mfma_f32_16x16x32_bf16 v[116:119], v[196:199], v[204:207], v[116:119]
	v_mfma_f32_16x16x32_bf16 v[104:107], v[168:171], v[212:215], v[104:107]
	v_mfma_f32_16x16x32_bf16 v[100:103], v[196:199], v[212:215], v[100:103]
	v_mfma_f32_16x16x32_bf16 v[88:91], v[168:171], v[220:223], v[88:91]
	v_mfma_f32_16x16x32_bf16 v[84:87], v[196:199], v[220:223], v[84:87]
	v_mfma_f32_16x16x32_bf16 v[72:75], v[168:171], v[228:231], v[72:75]
	v_mfma_f32_16x16x32_bf16 v[68:71], v[196:199], v[228:231], v[68:71]
	v_mfma_f32_16x16x32_bf16 v[120:123], v[172:175], v[208:211], v[120:123]
	v_mfma_f32_16x16x32_bf16 v[116:119], v[200:203], v[208:211], v[116:119]
	v_mfma_f32_16x16x32_bf16 v[104:107], v[172:175], v[216:219], v[104:107]
	v_mfma_f32_16x16x32_bf16 v[100:103], v[200:203], v[216:219], v[100:103]
	v_mfma_f32_16x16x32_bf16 v[88:91], v[172:175], v[224:227], v[88:91]
	v_mfma_f32_16x16x32_bf16 v[84:87], v[200:203], v[224:227], v[84:87]
	v_mfma_f32_16x16x32_bf16 v[72:75], v[172:175], v[232:235], v[72:75]
	v_mfma_f32_16x16x32_bf16 v[68:71], v[200:203], v[232:235], v[68:71]
	s_barrier
	s_add_i32 s16, s28, s58
	v_lshl_add_u64 v[152:153], v[152:153], 0, s[84:85]
	s_mov_b32 m0, s16
	ds_read_b128 v[204:207], v194 offset:49152
	ds_read_b128 v[208:211], v194 offset:50176
	ds_read_b128 v[212:215], v194 offset:51200
	ds_read_b128 v[216:219], v194 offset:52224
	ds_read_b128 v[220:223], v194 offset:53248
	ds_read_b128 v[224:227], v194 offset:54272
	ds_read_b128 v[228:231], v194 offset:55296
	ds_read_b128 v[232:235], v194 offset:56320
	global_load_lds_dwordx4 v[152:153], off
	s_add_i32 m0, s16, 0x2000
	s_add_u32 s14, s14, 0x40080
	v_lshl_add_u64 v[152:153], v[236:237], 0, s[84:85]
	s_addc_u32 s15, s15, 0
	s_add_i32 s16, s31, s58
	global_load_lds_dwordx4 v[152:153], off
	v_lshl_add_u64 v[152:153], s[14:15], 0, v[140:141]
	s_mov_b32 m0, s16
	s_nop 0
	global_load_lds_dwordx4 v[152:153], off
	v_lshl_add_u64 v[152:153], s[14:15], 0, v[144:145]
	s_add_i32 m0, s16, 0x2000
	s_nop 0
	global_load_lds_dwordx4 v[152:153], off
	v_lshl_add_u64 v[152:153], v[238:239], 0, s[84:85]
	s_mov_b32 m0, s18
	s_nop 0
	global_load_lds_dwordx4 v[152:153], off
	v_lshl_add_u64 v[152:153], v[240:241], 0, s[84:85]
	s_mov_b32 m0, s46
	s_nop 0
	global_load_lds_dwordx4 v[152:153], off
	s_waitcnt vmcnt(8)
	s_waitcnt lgkmcnt(0)
	s_barrier
	s_waitcnt lgkmcnt(0)
	v_mfma_f32_16x16x32_bf16 v[64:67], v[132:135], v[204:207], v[64:67]
	v_mfma_f32_16x16x32_bf16 v[60:63], v[160:163], v[204:207], v[60:63]
	v_mfma_f32_16x16x32_bf16 v[48:51], v[132:135], v[212:215], v[48:51]
	v_mfma_f32_16x16x32_bf16 v[44:47], v[160:163], v[212:215], v[44:47]
	v_mfma_f32_16x16x32_bf16 v[32:35], v[132:135], v[220:223], v[32:35]
	v_mfma_f32_16x16x32_bf16 v[28:31], v[160:163], v[220:223], v[28:31]
	v_mfma_f32_16x16x32_bf16 v[16:19], v[132:135], v[228:231], v[16:19]
	v_mfma_f32_16x16x32_bf16 v[12:15], v[160:163], v[228:231], v[12:15]
	v_mfma_f32_16x16x32_bf16 v[64:67], v[136:139], v[208:211], v[64:67]
	v_mfma_f32_16x16x32_bf16 v[60:63], v[164:167], v[208:211], v[60:63]
	v_mfma_f32_16x16x32_bf16 v[48:51], v[136:139], v[216:219], v[48:51]
	v_mfma_f32_16x16x32_bf16 v[44:47], v[164:167], v[216:219], v[44:47]
	v_mfma_f32_16x16x32_bf16 v[32:35], v[136:139], v[224:227], v[32:35]
	v_mfma_f32_16x16x32_bf16 v[28:31], v[164:167], v[224:227], v[28:31]
	v_mfma_f32_16x16x32_bf16 v[16:19], v[136:139], v[232:235], v[16:19]
	v_mfma_f32_16x16x32_bf16 v[12:15], v[164:167], v[232:235], v[12:15]
	v_mfma_f32_16x16x32_bf16 v[56:59], v[168:171], v[204:207], v[56:59]
	v_mfma_f32_16x16x32_bf16 v[52:55], v[196:199], v[204:207], v[52:55]
	v_mfma_f32_16x16x32_bf16 v[40:43], v[168:171], v[212:215], v[40:43]
	v_mfma_f32_16x16x32_bf16 v[36:39], v[196:199], v[212:215], v[36:39]
	v_mfma_f32_16x16x32_bf16 v[24:27], v[168:171], v[220:223], v[24:27]
	v_mfma_f32_16x16x32_bf16 v[20:23], v[196:199], v[220:223], v[20:23]
	v_mfma_f32_16x16x32_bf16 v[8:11], v[168:171], v[228:231], v[8:11]
	v_mfma_f32_16x16x32_bf16 v[4:7], v[196:199], v[228:231], v[4:7]
	v_mfma_f32_16x16x32_bf16 v[56:59], v[172:175], v[208:211], v[56:59]
	v_mfma_f32_16x16x32_bf16 v[52:55], v[200:203], v[208:211], v[52:55]
	v_mfma_f32_16x16x32_bf16 v[40:43], v[172:175], v[216:219], v[40:43]
	v_mfma_f32_16x16x32_bf16 v[36:39], v[200:203], v[216:219], v[36:39]
	v_mfma_f32_16x16x32_bf16 v[24:27], v[172:175], v[224:227], v[24:27]
	v_mfma_f32_16x16x32_bf16 v[20:23], v[200:203], v[224:227], v[20:23]
	v_mfma_f32_16x16x32_bf16 v[8:11], v[172:175], v[232:235], v[8:11]
	v_mfma_f32_16x16x32_bf16 v[4:7], v[200:203], v[232:235], v[4:7]
	s_add_i32 s27, s27, 2
	s_add_u32 s23, s23, 0x100
	s_addc_u32 s24, s24, 0
	s_add_u32 s12, s12, 0x100
	s_addc_u32 s13, s13, 0
	s_cmp_gt_u32 s27, 13
	s_barrier
	s_cbranch_scc0 .LBB0_437
	s_setprio 0
	s_and_b64 vcc, exec, s[48:49]
	s_cbranch_vccz .LBB0_440
	s_barrier

.Lsp_done_2:
.LBB0_620:
	s_add_u32 s16, s14, 0xfffc0080
	s_addc_u32 s17, s15, -1
	s_add_i32 s31, 0, 0x10000
	s_cmp_eq_u32 s27, 12
	s_cselect_b32 s19, s11, s17
	s_cselect_b32 s18, s22, s16
	v_add_u32_e32 v152, s31, v146
	s_cselect_b32 s17, s9, s24
	s_cselect_b32 s16, s28, s23
	s_add_i32 s41, 0, 0x14000
	ds_read_b128 v[142:145], v152
	ds_read_b128 v[160:163], v152 offset:1024
	ds_read_b128 v[164:167], v152 offset:2048
	ds_read_b128 v[168:171], v152 offset:3072
	v_add_u32_e32 v152, s41, v146
	ds_read_b128 v[172:175], v152
	ds_read_b128 v[190:193], v152 offset:1024
	ds_read_b128 v[194:197], v152 offset:2048
	ds_read_b128 v[198:201], v152 offset:3072
	v_lshl_add_u64 v[152:153], s[14:15], 0, v[140:141]
	s_add_i32 m0, s13, 0xc000
	ds_read_b128 v[202:205], v158
	ds_read_b128 v[206:209], v158 offset:1024
	ds_read_b128 v[210:213], v158 offset:2048
	ds_read_b128 v[214:217], v158 offset:3072
	ds_read_b128 v[218:221], v158 offset:4096
	ds_read_b128 v[222:225], v158 offset:5120
	ds_read_b128 v[226:229], v158 offset:6144
	ds_read_b128 v[230:233], v158 offset:7168
	global_load_lds_dwordx4 v[152:153], off
	v_lshl_add_u64 v[152:153], s[14:15], 0, v[138:139]
	s_add_i32 m0, s13, 0xe000
	s_nop 0
	global_load_lds_dwordx4 v[152:153], off
	s_waitcnt vmcnt(8)
	s_waitcnt lgkmcnt(0)
	s_barrier
	s_waitcnt lgkmcnt(0)
	v_mfma_f32_16x16x32_bf16 v[128:131], v[142:145], v[202:205], v[128:131]
	v_mfma_f32_16x16x32_bf16 v[120:123], v[164:167], v[202:205], v[120:123]
	v_mfma_f32_16x16x32_bf16 v[112:115], v[142:145], v[210:213], v[112:115]
	v_mfma_f32_16x16x32_bf16 v[104:107], v[164:167], v[210:213], v[104:107]
	v_mfma_f32_16x16x32_bf16 v[96:99], v[142:145], v[218:221], v[96:99]
	v_mfma_f32_16x16x32_bf16 v[88:91], v[164:167], v[218:221], v[88:91]
	v_mfma_f32_16x16x32_bf16 v[80:83], v[142:145], v[226:229], v[80:83]
	v_mfma_f32_16x16x32_bf16 v[72:75], v[164:167], v[226:229], v[72:75]
	v_mfma_f32_16x16x32_bf16 v[128:131], v[160:163], v[206:209], v[128:131]
	v_mfma_f32_16x16x32_bf16 v[120:123], v[168:171], v[206:209], v[120:123]
	v_mfma_f32_16x16x32_bf16 v[112:115], v[160:163], v[214:217], v[112:115]
	v_mfma_f32_16x16x32_bf16 v[104:107], v[168:171], v[214:217], v[104:107]
	v_mfma_f32_16x16x32_bf16 v[96:99], v[160:163], v[222:225], v[96:99]
	v_mfma_f32_16x16x32_bf16 v[88:91], v[168:171], v[222:225], v[88:91]
	v_mfma_f32_16x16x32_bf16 v[80:83], v[160:163], v[230:233], v[80:83]
	v_mfma_f32_16x16x32_bf16 v[72:75], v[168:171], v[230:233], v[72:75]
	v_mfma_f32_16x16x32_bf16 v[124:127], v[172:175], v[202:205], v[124:127]
	v_mfma_f32_16x16x32_bf16 v[116:119], v[194:197], v[202:205], v[116:119]
	v_mfma_f32_16x16x32_bf16 v[108:111], v[172:175], v[210:213], v[108:111]
	v_mfma_f32_16x16x32_bf16 v[100:103], v[194:197], v[210:213], v[100:103]
	v_mfma_f32_16x16x32_bf16 v[92:95], v[172:175], v[218:221], v[92:95]
	v_mfma_f32_16x16x32_bf16 v[84:87], v[194:197], v[218:221], v[84:87]
	v_mfma_f32_16x16x32_bf16 v[76:79], v[172:175], v[226:229], v[76:79]
	v_mfma_f32_16x16x32_bf16 v[68:71], v[194:197], v[226:229], v[68:71]
	v_mfma_f32_16x16x32_bf16 v[124:127], v[190:193], v[206:209], v[124:127]
	v_mfma_f32_16x16x32_bf16 v[116:119], v[198:201], v[206:209], v[116:119]
	v_mfma_f32_16x16x32_bf16 v[108:111], v[190:193], v[214:217], v[108:111]
	v_mfma_f32_16x16x32_bf16 v[100:103], v[198:201], v[214:217], v[100:103]
	v_mfma_f32_16x16x32_bf16 v[92:95], v[190:193], v[222:225], v[92:95]
	v_mfma_f32_16x16x32_bf16 v[84:87], v[198:201], v[222:225], v[84:87]
	v_mfma_f32_16x16x32_bf16 v[76:79], v[190:193], v[230:233], v[76:79]
	v_mfma_f32_16x16x32_bf16 v[68:71], v[198:201], v[230:233], v[68:71]
	s_barrier
	s_add_i32 s31, s31, s52
	v_lshl_add_u64 v[152:153], s[16:17], 0, v[132:133]
	s_mov_b32 m0, s31
	ds_read_b128 v[202:205], v158 offset:16384
	ds_read_b128 v[206:209], v158 offset:17408
	ds_read_b128 v[210:213], v158 offset:18432
	ds_read_b128 v[214:217], v158 offset:19456
	ds_read_b128 v[218:221], v158 offset:20480
	ds_read_b128 v[222:225], v158 offset:21504
	ds_read_b128 v[226:229], v158 offset:22528
	ds_read_b128 v[230:233], v158 offset:23552
	global_load_lds_dwordx4 v[152:153], off
	s_add_i32 m0, s31, 0x2000
	s_add_u32 s36, s16, 0x40000
	v_lshl_add_u64 v[234:235], s[16:17], 0, v[136:137]
	s_addc_u32 s37, s17, 0
	s_add_i32 s31, s41, s52
	global_load_lds_dwordx4 v[234:235], off
	v_lshl_add_u64 v[236:237], s[36:37], 0, v[132:133]
	s_mov_b32 m0, s31
	v_lshl_add_u64 v[238:239], s[18:19], 0, v[134:135]
	global_load_lds_dwordx4 v[236:237], off
	v_lshl_add_u64 v[236:237], s[36:37], 0, v[136:137]
	s_add_i32 m0, s31, 0x2000
	s_nop 0
	global_load_lds_dwordx4 v[236:237], off
	v_lshl_add_u64 v[236:237], s[18:19], 0, v[0:1]
	s_mov_b32 m0, s13
	s_nop 0
	global_load_lds_dwordx4 v[236:237], off
	s_mov_b32 m0, s53
	s_nop 0
	global_load_lds_dwordx4 v[238:239], off
	s_waitcnt vmcnt(8)
	s_waitcnt lgkmcnt(0)
	s_barrier
	s_waitcnt lgkmcnt(0)
	v_mfma_f32_16x16x32_bf16 v[64:67], v[142:145], v[202:205], v[64:67]
	v_mfma_f32_16x16x32_bf16 v[56:59], v[164:167], v[202:205], v[56:59]
	v_mfma_f32_16x16x32_bf16 v[48:51], v[142:145], v[210:213], v[48:51]
	v_mfma_f32_16x16x32_bf16 v[40:43], v[164:167], v[210:213], v[40:43]
	v_mfma_f32_16x16x32_bf16 v[32:35], v[142:145], v[218:221], v[32:35]
	v_mfma_f32_16x16x32_bf16 v[24:27], v[164:167], v[218:221], v[24:27]
	v_mfma_f32_16x16x32_bf16 v[16:19], v[142:145], v[226:229], v[16:19]
	v_mfma_f32_16x16x32_bf16 v[8:11], v[164:167], v[226:229], v[8:11]
	v_mfma_f32_16x16x32_bf16 v[64:67], v[160:163], v[206:209], v[64:67]
	v_mfma_f32_16x16x32_bf16 v[56:59], v[168:171], v[206:209], v[56:59]
	v_mfma_f32_16x16x32_bf16 v[48:51], v[160:163], v[214:217], v[48:51]
	v_mfma_f32_16x16x32_bf16 v[40:43], v[168:171], v[214:217], v[40:43]
	v_mfma_f32_16x16x32_bf16 v[32:35], v[160:163], v[222:225], v[32:35]
	v_mfma_f32_16x16x32_bf16 v[24:27], v[168:171], v[222:225], v[24:27]
	v_mfma_f32_16x16x32_bf16 v[16:19], v[160:163], v[230:233], v[16:19]
	v_mfma_f32_16x16x32_bf16 v[8:11], v[168:171], v[230:233], v[8:11]
	v_mfma_f32_16x16x32_bf16 v[60:63], v[172:175], v[202:205], v[60:63]
	v_mfma_f32_16x16x32_bf16 v[52:55], v[194:197], v[202:205], v[52:55]
	v_mfma_f32_16x16x32_bf16 v[44:47], v[172:175], v[210:213], v[44:47]
	v_mfma_f32_16x16x32_bf16 v[36:39], v[194:197], v[210:213], v[36:39]
	v_mfma_f32_16x16x32_bf16 v[28:31], v[172:175], v[218:221], v[28:31]
	v_mfma_f32_16x16x32_bf16 v[20:23], v[194:197], v[218:221], v[20:23]
	v_mfma_f32_16x16x32_bf16 v[12:15], v[172:175], v[226:229], v[12:15]
	v_mfma_f32_16x16x32_bf16 v[4:7], v[194:197], v[226:229], v[4:7]
	v_mfma_f32_16x16x32_bf16 v[60:63], v[190:193], v[206:209], v[60:63]
	v_mfma_f32_16x16x32_bf16 v[52:55], v[198:201], v[206:209], v[52:55]
	v_mfma_f32_16x16x32_bf16 v[44:47], v[190:193], v[214:217], v[44:47]
	v_mfma_f32_16x16x32_bf16 v[36:39], v[198:201], v[214:217], v[36:39]
	v_mfma_f32_16x16x32_bf16 v[28:31], v[190:193], v[222:225], v[28:31]
	v_mfma_f32_16x16x32_bf16 v[20:23], v[198:201], v[222:225], v[20:23]
	v_mfma_f32_16x16x32_bf16 v[12:15], v[190:193], v[230:233], v[12:15]
	v_mfma_f32_16x16x32_bf16 v[4:7], v[198:201], v[230:233], v[4:7]
	s_barrier
	s_add_i32 s31, 0, 0x18000
	v_add_u32_e32 v159, s31, v146
	s_add_i32 s36, 0, 0x1c000
	ds_read_b128 v[142:145], v159
	ds_read_b128 v[160:163], v159 offset:1024
	ds_read_b128 v[164:167], v159 offset:2048
	ds_read_b128 v[168:171], v159 offset:3072
	v_add_u32_e32 v159, s36, v146
	ds_read_b128 v[172:175], v159
	ds_read_b128 v[190:193], v159 offset:1024
	ds_read_b128 v[194:197], v159 offset:2048
	ds_read_b128 v[198:201], v159 offset:3072
	s_add_u32 s18, s18, 0x40000
	s_addc_u32 s19, s19, 0
	s_mov_b32 m0, s54
	v_lshl_add_u64 v[240:241], s[18:19], 0, v[0:1]
	ds_read_b128 v[202:205], v158 offset:32768
	ds_read_b128 v[206:209], v158 offset:33792
	ds_read_b128 v[210:213], v158 offset:34816
	ds_read_b128 v[214:217], v158 offset:35840
	ds_read_b128 v[218:221], v158 offset:36864
	ds_read_b128 v[222:225], v158 offset:37888
	ds_read_b128 v[226:229], v158 offset:38912
	ds_read_b128 v[230:233], v158 offset:39936
	global_load_lds_dwordx4 v[240:241], off
	v_lshl_add_u64 v[240:241], s[18:19], 0, v[134:135]
	s_mov_b32 m0, s55
	s_nop 0
	global_load_lds_dwordx4 v[240:241], off
	s_waitcnt vmcnt(8)
	s_waitcnt lgkmcnt(0)
	s_barrier
	s_waitcnt lgkmcnt(0)
	v_mfma_f32_16x16x32_bf16 v[128:131], v[142:145], v[202:205], v[128:131]
	v_mfma_f32_16x16x32_bf16 v[120:123], v[164:167], v[202:205], v[120:123]
	v_mfma_f32_16x16x32_bf16 v[112:115], v[142:145], v[210:213], v[112:115]
	v_mfma_f32_16x16x32_bf16 v[104:107], v[164:167], v[210:213], v[104:107]
	v_mfma_f32_16x16x32_bf16 v[96:99], v[142:145], v[218:221], v[96:99]
	v_mfma_f32_16x16x32_bf16 v[88:91], v[164:167], v[218:221], v[88:91]
	v_mfma_f32_16x16x32_bf16 v[80:83], v[142:145], v[226:229], v[80:83]
	v_mfma_f32_16x16x32_bf16 v[72:75], v[164:167], v[226:229], v[72:75]
	v_mfma_f32_16x16x32_bf16 v[128:131], v[160:163], v[206:209], v[128:131]
	v_mfma_f32_16x16x32_bf16 v[120:123], v[168:171], v[206:209], v[120:123]
	v_mfma_f32_16x16x32_bf16 v[112:115], v[160:163], v[214:217], v[112:115]
	v_mfma_f32_16x16x32_bf16 v[104:107], v[168:171], v[214:217], v[104:107]
	v_mfma_f32_16x16x32_bf16 v[96:99], v[160:163], v[222:225], v[96:99]
	v_mfma_f32_16x16x32_bf16 v[88:91], v[168:171], v[222:225], v[88:91]
	v_mfma_f32_16x16x32_bf16 v[80:83], v[160:163], v[230:233], v[80:83]
	v_mfma_f32_16x16x32_bf16 v[72:75], v[168:171], v[230:233], v[72:75]
	v_mfma_f32_16x16x32_bf16 v[124:127], v[172:175], v[202:205], v[124:127]
	v_mfma_f32_16x16x32_bf16 v[116:119], v[194:197], v[202:205], v[116:119]
	v_mfma_f32_16x16x32_bf16 v[108:111], v[172:175], v[210:213], v[108:111]
	v_mfma_f32_16x16x32_bf16 v[100:103], v[194:197], v[210:213], v[100:103]
	v_mfma_f32_16x16x32_bf16 v[92:95], v[172:175], v[218:221], v[92:95]
	v_mfma_f32_16x16x32_bf16 v[84:87], v[194:197], v[218:221], v[84:87]
	v_mfma_f32_16x16x32_bf16 v[76:79], v[172:175], v[226:229], v[76:79]
	v_mfma_f32_16x16x32_bf16 v[68:71], v[194:197], v[226:229], v[68:71]
	v_mfma_f32_16x16x32_bf16 v[124:127], v[190:193], v[206:209], v[124:127]
	v_mfma_f32_16x16x32_bf16 v[116:119], v[198:201], v[206:209], v[116:119]
	v_mfma_f32_16x16x32_bf16 v[108:111], v[190:193], v[214:217], v[108:111]
	v_mfma_f32_16x16x32_bf16 v[100:103], v[198:201], v[214:217], v[100:103]
	v_mfma_f32_16x16x32_bf16 v[92:95], v[190:193], v[222:225], v[92:95]
	v_mfma_f32_16x16x32_bf16 v[84:87], v[198:201], v[222:225], v[84:87]
	v_mfma_f32_16x16x32_bf16 v[76:79], v[190:193], v[230:233], v[76:79]
	v_mfma_f32_16x16x32_bf16 v[68:71], v[198:201], v[230:233], v[68:71]
	s_barrier
	s_add_i32 s18, s31, s52
	v_lshl_add_u64 v[152:153], v[152:153], 0, s[84:85]
	s_mov_b32 m0, s18
	ds_read_b128 v[202:205], v158 offset:49152
	ds_read_b128 v[206:209], v158 offset:50176
	ds_read_b128 v[210:213], v158 offset:51200
	ds_read_b128 v[214:217], v158 offset:52224
	ds_read_b128 v[218:221], v158 offset:53248
	ds_read_b128 v[222:225], v158 offset:54272
	ds_read_b128 v[226:229], v158 offset:55296
	ds_read_b128 v[230:233], v158 offset:56320
	global_load_lds_dwordx4 v[152:153], off
	s_add_i32 m0, s18, 0x2000
	s_add_u32 s16, s16, 0x40080
	v_lshl_add_u64 v[152:153], v[234:235], 0, s[84:85]
	s_addc_u32 s17, s17, 0
	s_add_i32 s18, s36, s52
	global_load_lds_dwordx4 v[152:153], off
	v_lshl_add_u64 v[152:153], s[16:17], 0, v[132:133]
	s_mov_b32 m0, s18
	s_nop 0
	global_load_lds_dwordx4 v[152:153], off
	v_lshl_add_u64 v[152:153], s[16:17], 0, v[136:137]
	s_add_i32 m0, s18, 0x2000
	s_nop 0
	global_load_lds_dwordx4 v[152:153], off
	v_lshl_add_u64 v[152:153], v[236:237], 0, s[84:85]
	s_mov_b32 m0, s58
	s_nop 0
	global_load_lds_dwordx4 v[152:153], off
	v_lshl_add_u64 v[152:153], v[238:239], 0, s[84:85]
	s_mov_b32 m0, s59
	s_nop 0
	global_load_lds_dwordx4 v[152:153], off
	s_waitcnt vmcnt(8)
	s_waitcnt lgkmcnt(0)
	s_barrier
	s_waitcnt lgkmcnt(0)
	v_mfma_f32_16x16x32_bf16 v[64:67], v[142:145], v[202:205], v[64:67]
	v_mfma_f32_16x16x32_bf16 v[56:59], v[164:167], v[202:205], v[56:59]
	v_mfma_f32_16x16x32_bf16 v[48:51], v[142:145], v[210:213], v[48:51]
	v_mfma_f32_16x16x32_bf16 v[40:43], v[164:167], v[210:213], v[40:43]
	v_mfma_f32_16x16x32_bf16 v[32:35], v[142:145], v[218:221], v[32:35]
	v_mfma_f32_16x16x32_bf16 v[24:27], v[164:167], v[218:221], v[24:27]
	v_mfma_f32_16x16x32_bf16 v[16:19], v[142:145], v[226:229], v[16:19]
	v_mfma_f32_16x16x32_bf16 v[8:11], v[164:167], v[226:229], v[8:11]
	v_mfma_f32_16x16x32_bf16 v[64:67], v[160:163], v[206:209], v[64:67]
	v_mfma_f32_16x16x32_bf16 v[56:59], v[168:171], v[206:209], v[56:59]
	v_mfma_f32_16x16x32_bf16 v[48:51], v[160:163], v[214:217], v[48:51]
	v_mfma_f32_16x16x32_bf16 v[40:43], v[168:171], v[214:217], v[40:43]
	v_mfma_f32_16x16x32_bf16 v[32:35], v[160:163], v[222:225], v[32:35]
	v_mfma_f32_16x16x32_bf16 v[24:27], v[168:171], v[222:225], v[24:27]
	v_mfma_f32_16x16x32_bf16 v[16:19], v[160:163], v[230:233], v[16:19]
	v_mfma_f32_16x16x32_bf16 v[8:11], v[168:171], v[230:233], v[8:11]
	v_mfma_f32_16x16x32_bf16 v[60:63], v[172:175], v[202:205], v[60:63]
	v_mfma_f32_16x16x32_bf16 v[52:55], v[194:197], v[202:205], v[52:55]
	v_mfma_f32_16x16x32_bf16 v[44:47], v[172:175], v[210:213], v[44:47]
	v_mfma_f32_16x16x32_bf16 v[36:39], v[194:197], v[210:213], v[36:39]
	v_mfma_f32_16x16x32_bf16 v[28:31], v[172:175], v[218:221], v[28:31]
	v_mfma_f32_16x16x32_bf16 v[20:23], v[194:197], v[218:221], v[20:23]
	v_mfma_f32_16x16x32_bf16 v[12:15], v[172:175], v[226:229], v[12:15]
	v_mfma_f32_16x16x32_bf16 v[4:7], v[194:197], v[226:229], v[4:7]
	v_mfma_f32_16x16x32_bf16 v[60:63], v[190:193], v[206:209], v[60:63]
	v_mfma_f32_16x16x32_bf16 v[52:55], v[198:201], v[206:209], v[52:55]
	v_mfma_f32_16x16x32_bf16 v[44:47], v[190:193], v[214:217], v[44:47]
	v_mfma_f32_16x16x32_bf16 v[36:39], v[198:201], v[214:217], v[36:39]
	v_mfma_f32_16x16x32_bf16 v[28:31], v[190:193], v[222:225], v[28:31]
	v_mfma_f32_16x16x32_bf16 v[20:23], v[198:201], v[222:225], v[20:23]
	v_mfma_f32_16x16x32_bf16 v[12:15], v[190:193], v[230:233], v[12:15]
	v_mfma_f32_16x16x32_bf16 v[4:7], v[198:201], v[230:233], v[4:7]
	s_add_i32 s27, s27, 2
	s_add_u32 s23, s23, 0x100
	s_addc_u32 s24, s24, 0
	s_add_u32 s14, s14, 0x100
	s_addc_u32 s15, s15, 0
	s_cmp_gt_u32 s27, 13
	s_barrier
	s_cbranch_scc0 .LBB0_620
	s_setprio 0
	s_and_b64 vcc, exec, s[6:7]
	s_cbranch_vccz .LBB0_623
	s_barrier

.Lsp_done_3:
.LBB0_676:
	s_add_i32 s24, s12, 2
	s_add_u32 s27, s10, 0x80
	s_addc_u32 s13, s11, 0
	s_add_i32 s31, 0, 0x10000
	s_cmp_eq_u32 s14, s12
	s_cselect_b32 s13, s1, s13
	s_cselect_b32 s12, s0, s27
	s_cselect_b32 s37, s49, s23
	s_cselect_b32 s36, s48, s15
	s_add_i32 s27, 0, 0x14000
	v_add_u32_e32 v144, s31, v170
	v_add_u32_e32 v152, s27, v170
	ds_read_b128 v[128:131], v144
	ds_read_b128 v[132:135], v144 offset:1024
	ds_read_b128 v[136:139], v144 offset:2048
	ds_read_b128 v[144:147], v144 offset:3072
	ds_read_b128 v[164:167], v152
	ds_read_b128 v[190:193], v152 offset:1024
	ds_read_b128 v[194:197], v152 offset:2048
	ds_read_b128 v[198:201], v152 offset:3072
	v_lshl_add_u64 v[152:153], s[10:11], 0, v[162:163]
	s_add_i32 m0, s51, 0xc000
	ds_read_b128 v[202:205], v172
	ds_read_b128 v[206:209], v172 offset:1024
	ds_read_b128 v[210:213], v172 offset:2048
	ds_read_b128 v[214:217], v172 offset:3072
	ds_read_b128 v[218:221], v172 offset:4096
	ds_read_b128 v[222:225], v172 offset:5120
	ds_read_b128 v[226:229], v172 offset:6144
	ds_read_b128 v[230:233], v172 offset:7168
	global_load_lds_dwordx4 v[152:153], off
	v_lshl_add_u64 v[152:153], s[10:11], 0, v[160:161]
	s_add_i32 m0, s51, 0xe000
	s_nop 0
	global_load_lds_dwordx4 v[152:153], off
	s_waitcnt vmcnt(8)
	s_waitcnt lgkmcnt(0)
	s_barrier
	s_waitcnt lgkmcnt(0)
	v_mfma_f32_16x16x32_bf16 v[140:143], v[128:131], v[202:205], v[140:143]
	v_mfma_f32_16x16x32_bf16 v[124:127], v[136:139], v[202:205], v[124:127]
	v_mfma_f32_16x16x32_bf16 v[112:115], v[128:131], v[210:213], v[112:115]
	v_mfma_f32_16x16x32_bf16 v[108:111], v[136:139], v[210:213], v[108:111]
	v_mfma_f32_16x16x32_bf16 v[96:99], v[128:131], v[218:221], v[96:99]
	v_mfma_f32_16x16x32_bf16 v[92:95], v[136:139], v[218:221], v[92:95]
	v_mfma_f32_16x16x32_bf16 v[80:83], v[128:131], v[226:229], v[80:83]
	v_mfma_f32_16x16x32_bf16 v[76:79], v[136:139], v[226:229], v[76:79]
	v_mfma_f32_16x16x32_bf16 v[140:143], v[132:135], v[206:209], v[140:143]
	v_mfma_f32_16x16x32_bf16 v[124:127], v[144:147], v[206:209], v[124:127]
	v_mfma_f32_16x16x32_bf16 v[112:115], v[132:135], v[214:217], v[112:115]
	v_mfma_f32_16x16x32_bf16 v[108:111], v[144:147], v[214:217], v[108:111]
	v_mfma_f32_16x16x32_bf16 v[96:99], v[132:135], v[222:225], v[96:99]
	v_mfma_f32_16x16x32_bf16 v[92:95], v[144:147], v[222:225], v[92:95]
	v_mfma_f32_16x16x32_bf16 v[80:83], v[132:135], v[230:233], v[80:83]
	v_mfma_f32_16x16x32_bf16 v[76:79], v[144:147], v[230:233], v[76:79]
	v_mfma_f32_16x16x32_bf16 v[120:123], v[164:167], v[202:205], v[120:123]
	v_mfma_f32_16x16x32_bf16 v[116:119], v[194:197], v[202:205], v[116:119]
	v_mfma_f32_16x16x32_bf16 v[104:107], v[164:167], v[210:213], v[104:107]
	v_mfma_f32_16x16x32_bf16 v[100:103], v[194:197], v[210:213], v[100:103]
	v_mfma_f32_16x16x32_bf16 v[88:91], v[164:167], v[218:221], v[88:91]
	v_mfma_f32_16x16x32_bf16 v[84:87], v[194:197], v[218:221], v[84:87]
	v_mfma_f32_16x16x32_bf16 v[72:75], v[164:167], v[226:229], v[72:75]
	v_mfma_f32_16x16x32_bf16 v[68:71], v[194:197], v[226:229], v[68:71]
	v_mfma_f32_16x16x32_bf16 v[120:123], v[190:193], v[206:209], v[120:123]
	v_mfma_f32_16x16x32_bf16 v[116:119], v[198:201], v[206:209], v[116:119]
	v_mfma_f32_16x16x32_bf16 v[104:107], v[190:193], v[214:217], v[104:107]
	v_mfma_f32_16x16x32_bf16 v[100:103], v[198:201], v[214:217], v[100:103]
	v_mfma_f32_16x16x32_bf16 v[88:91], v[190:193], v[222:225], v[88:91]
	v_mfma_f32_16x16x32_bf16 v[84:87], v[198:201], v[222:225], v[84:87]
	v_mfma_f32_16x16x32_bf16 v[72:75], v[190:193], v[230:233], v[72:75]
	v_mfma_f32_16x16x32_bf16 v[68:71], v[198:201], v[230:233], v[68:71]
	s_barrier
	s_add_i32 s31, s31, s19
	v_lshl_add_u64 v[152:153], s[36:37], 0, v[0:1]
	s_mov_b32 m0, s31
	ds_read_b128 v[202:205], v172 offset:16384
	ds_read_b128 v[206:209], v172 offset:17408
	ds_read_b128 v[210:213], v172 offset:18432
	ds_read_b128 v[214:217], v172 offset:19456
	ds_read_b128 v[218:221], v172 offset:20480
	ds_read_b128 v[222:225], v172 offset:21504
	ds_read_b128 v[226:229], v172 offset:22528
	ds_read_b128 v[230:233], v172 offset:23552
	global_load_lds_dwordx4 v[152:153], off
	s_add_i32 m0, s31, 0x2000
	v_lshl_add_u64 v[168:169], s[36:37], 0, v[158:159]
	s_add_u32 s36, s36, s88
	s_addc_u32 s37, s37, 0
	s_add_i32 s27, s27, s19
	global_load_lds_dwordx4 v[168:169], off
	v_lshl_add_u64 v[174:175], s[36:37], 0, v[0:1]
	s_mov_b32 m0, s27
	v_lshl_add_u64 v[234:235], s[36:37], 0, v[158:159]
	global_load_lds_dwordx4 v[174:175], off
	s_add_i32 m0, s27, 0x2000
	v_lshl_add_u64 v[236:237], s[12:13], 0, v[0:1]
	global_load_lds_dwordx4 v[234:235], off
	s_mov_b32 m0, s51
	v_lshl_add_u64 v[238:239], s[12:13], 0, v[158:159]
	global_load_lds_dwordx4 v[236:237], off
	s_mov_b32 m0, s52
	s_nop 0
	global_load_lds_dwordx4 v[238:239], off
	s_waitcnt vmcnt(8)
	s_waitcnt lgkmcnt(0)
	s_barrier
	s_waitcnt lgkmcnt(0)
	v_mfma_f32_16x16x32_bf16 v[64:67], v[128:131], v[202:205], v[64:67]
	v_mfma_f32_16x16x32_bf16 v[60:63], v[136:139], v[202:205], v[60:63]
	v_mfma_f32_16x16x32_bf16 v[48:51], v[128:131], v[210:213], v[48:51]
	v_mfma_f32_16x16x32_bf16 v[44:47], v[136:139], v[210:213], v[44:47]
	v_mfma_f32_16x16x32_bf16 v[32:35], v[128:131], v[218:221], v[32:35]
	v_mfma_f32_16x16x32_bf16 v[28:31], v[136:139], v[218:221], v[28:31]
	v_mfma_f32_16x16x32_bf16 v[16:19], v[128:131], v[226:229], v[16:19]
	v_mfma_f32_16x16x32_bf16 v[12:15], v[136:139], v[226:229], v[12:15]
	v_mfma_f32_16x16x32_bf16 v[64:67], v[132:135], v[206:209], v[64:67]
	v_mfma_f32_16x16x32_bf16 v[60:63], v[144:147], v[206:209], v[60:63]
	v_mfma_f32_16x16x32_bf16 v[48:51], v[132:135], v[214:217], v[48:51]
	v_mfma_f32_16x16x32_bf16 v[44:47], v[144:147], v[214:217], v[44:47]
	v_mfma_f32_16x16x32_bf16 v[32:35], v[132:135], v[222:225], v[32:35]
	v_mfma_f32_16x16x32_bf16 v[28:31], v[144:147], v[222:225], v[28:31]
	v_mfma_f32_16x16x32_bf16 v[16:19], v[132:135], v[230:233], v[16:19]
	v_mfma_f32_16x16x32_bf16 v[12:15], v[144:147], v[230:233], v[12:15]
	v_mfma_f32_16x16x32_bf16 v[56:59], v[164:167], v[202:205], v[56:59]
	v_mfma_f32_16x16x32_bf16 v[52:55], v[194:197], v[202:205], v[52:55]
	v_mfma_f32_16x16x32_bf16 v[40:43], v[164:167], v[210:213], v[40:43]
	v_mfma_f32_16x16x32_bf16 v[36:39], v[194:197], v[210:213], v[36:39]
	v_mfma_f32_16x16x32_bf16 v[24:27], v[164:167], v[218:221], v[24:27]
	v_mfma_f32_16x16x32_bf16 v[20:23], v[194:197], v[218:221], v[20:23]
	v_mfma_f32_16x16x32_bf16 v[8:11], v[164:167], v[226:229], v[8:11]
	v_mfma_f32_16x16x32_bf16 v[4:7], v[194:197], v[226:229], v[4:7]
	v_mfma_f32_16x16x32_bf16 v[56:59], v[190:193], v[206:209], v[56:59]
	v_mfma_f32_16x16x32_bf16 v[52:55], v[198:201], v[206:209], v[52:55]
	v_mfma_f32_16x16x32_bf16 v[40:43], v[190:193], v[214:217], v[40:43]
	v_mfma_f32_16x16x32_bf16 v[36:39], v[198:201], v[214:217], v[36:39]
	v_mfma_f32_16x16x32_bf16 v[24:27], v[190:193], v[222:225], v[24:27]
	v_mfma_f32_16x16x32_bf16 v[20:23], v[198:201], v[222:225], v[20:23]
	v_mfma_f32_16x16x32_bf16 v[8:11], v[190:193], v[230:233], v[8:11]
	v_mfma_f32_16x16x32_bf16 v[4:7], v[198:201], v[230:233], v[4:7]
	s_barrier
	s_add_i32 s27, 0, 0x18000
	s_add_i32 s31, 0, 0x1c000
	v_add_u32_e32 v144, s27, v170
	v_add_u32_e32 v173, s31, v170
	ds_read_b128 v[128:131], v144
	ds_read_b128 v[132:135], v144 offset:1024
	ds_read_b128 v[136:139], v144 offset:2048
	ds_read_b128 v[144:147], v144 offset:3072
	ds_read_b128 v[164:167], v173
	ds_read_b128 v[190:193], v173 offset:1024
	ds_read_b128 v[194:197], v173 offset:2048
	ds_read_b128 v[198:201], v173 offset:3072
	s_add_u32 s12, s12, s88
	s_addc_u32 s13, s13, 0
	s_mov_b32 m0, s53
	v_lshl_add_u64 v[240:241], s[12:13], 0, v[0:1]
	ds_read_b128 v[202:205], v172 offset:32768
	ds_read_b128 v[206:209], v172 offset:33792
	ds_read_b128 v[210:213], v172 offset:34816
	ds_read_b128 v[214:217], v172 offset:35840
	ds_read_b128 v[218:221], v172 offset:36864
	ds_read_b128 v[222:225], v172 offset:37888
	ds_read_b128 v[226:229], v172 offset:38912
	ds_read_b128 v[230:233], v172 offset:39936
	global_load_lds_dwordx4 v[240:241], off
	v_lshl_add_u64 v[240:241], s[12:13], 0, v[158:159]
	s_mov_b32 m0, s54
	s_nop 0
	global_load_lds_dwordx4 v[240:241], off
	s_waitcnt vmcnt(8)
	s_waitcnt lgkmcnt(0)
	s_barrier
	s_waitcnt lgkmcnt(0)
	v_mfma_f32_16x16x32_bf16 v[140:143], v[128:131], v[202:205], v[140:143]
	v_mfma_f32_16x16x32_bf16 v[124:127], v[136:139], v[202:205], v[124:127]
	v_mfma_f32_16x16x32_bf16 v[112:115], v[128:131], v[210:213], v[112:115]
	v_mfma_f32_16x16x32_bf16 v[108:111], v[136:139], v[210:213], v[108:111]
	v_mfma_f32_16x16x32_bf16 v[96:99], v[128:131], v[218:221], v[96:99]
	v_mfma_f32_16x16x32_bf16 v[92:95], v[136:139], v[218:221], v[92:95]
	v_mfma_f32_16x16x32_bf16 v[80:83], v[128:131], v[226:229], v[80:83]
	v_mfma_f32_16x16x32_bf16 v[76:79], v[136:139], v[226:229], v[76:79]
	v_mfma_f32_16x16x32_bf16 v[140:143], v[132:135], v[206:209], v[140:143]
	v_mfma_f32_16x16x32_bf16 v[124:127], v[144:147], v[206:209], v[124:127]
	v_mfma_f32_16x16x32_bf16 v[112:115], v[132:135], v[214:217], v[112:115]
	v_mfma_f32_16x16x32_bf16 v[108:111], v[144:147], v[214:217], v[108:111]
	v_mfma_f32_16x16x32_bf16 v[96:99], v[132:135], v[222:225], v[96:99]
	v_mfma_f32_16x16x32_bf16 v[92:95], v[144:147], v[222:225], v[92:95]
	v_mfma_f32_16x16x32_bf16 v[80:83], v[132:135], v[230:233], v[80:83]
	v_mfma_f32_16x16x32_bf16 v[76:79], v[144:147], v[230:233], v[76:79]
	v_mfma_f32_16x16x32_bf16 v[120:123], v[164:167], v[202:205], v[120:123]
	v_mfma_f32_16x16x32_bf16 v[116:119], v[194:197], v[202:205], v[116:119]
	v_mfma_f32_16x16x32_bf16 v[104:107], v[164:167], v[210:213], v[104:107]
	v_mfma_f32_16x16x32_bf16 v[100:103], v[194:197], v[210:213], v[100:103]
	v_mfma_f32_16x16x32_bf16 v[88:91], v[164:167], v[218:221], v[88:91]
	v_mfma_f32_16x16x32_bf16 v[84:87], v[194:197], v[218:221], v[84:87]
	v_mfma_f32_16x16x32_bf16 v[72:75], v[164:167], v[226:229], v[72:75]
	v_mfma_f32_16x16x32_bf16 v[68:71], v[194:197], v[226:229], v[68:71]
	v_mfma_f32_16x16x32_bf16 v[120:123], v[190:193], v[206:209], v[120:123]
	v_mfma_f32_16x16x32_bf16 v[116:119], v[198:201], v[206:209], v[116:119]
	v_mfma_f32_16x16x32_bf16 v[104:107], v[190:193], v[214:217], v[104:107]
	v_mfma_f32_16x16x32_bf16 v[100:103], v[198:201], v[214:217], v[100:103]
	v_mfma_f32_16x16x32_bf16 v[88:91], v[190:193], v[222:225], v[88:91]
	v_mfma_f32_16x16x32_bf16 v[84:87], v[198:201], v[222:225], v[84:87]
	v_mfma_f32_16x16x32_bf16 v[72:75], v[190:193], v[230:233], v[72:75]
	v_mfma_f32_16x16x32_bf16 v[68:71], v[198:201], v[230:233], v[68:71]
	s_barrier
	s_add_i32 s12, s27, s19
	v_lshl_add_u64 v[152:153], v[152:153], 0, s[84:85]
	s_mov_b32 m0, s12
	ds_read_b128 v[202:205], v172 offset:49152
	ds_read_b128 v[206:209], v172 offset:50176
	ds_read_b128 v[210:213], v172 offset:51200
	ds_read_b128 v[214:217], v172 offset:52224
	ds_read_b128 v[218:221], v172 offset:53248
	ds_read_b128 v[222:225], v172 offset:54272
	ds_read_b128 v[226:229], v172 offset:55296
	ds_read_b128 v[230:233], v172 offset:56320
	global_load_lds_dwordx4 v[152:153], off
	v_lshl_add_u64 v[152:153], v[168:169], 0, s[84:85]
	s_add_i32 m0, s12, 0x2000
	s_add_i32 s12, s31, s19
	global_load_lds_dwordx4 v[152:153], off
	v_lshl_add_u64 v[152:153], v[174:175], 0, s[84:85]
	s_mov_b32 m0, s12
	s_nop 0
	global_load_lds_dwordx4 v[152:153], off
	v_lshl_add_u64 v[152:153], v[234:235], 0, s[84:85]
	s_add_i32 m0, s12, 0x2000
	s_nop 0
	global_load_lds_dwordx4 v[152:153], off
	v_lshl_add_u64 v[152:153], v[236:237], 0, s[84:85]
	s_mov_b32 m0, s55
	s_nop 0
	global_load_lds_dwordx4 v[152:153], off
	v_lshl_add_u64 v[152:153], v[238:239], 0, s[84:85]
	s_mov_b32 m0, s58
	s_nop 0
	global_load_lds_dwordx4 v[152:153], off
	s_waitcnt vmcnt(8)
	s_waitcnt lgkmcnt(0)
	s_barrier
	s_waitcnt lgkmcnt(0)
	v_mfma_f32_16x16x32_bf16 v[64:67], v[128:131], v[202:205], v[64:67]
	v_mfma_f32_16x16x32_bf16 v[60:63], v[136:139], v[202:205], v[60:63]
	v_mfma_f32_16x16x32_bf16 v[48:51], v[128:131], v[210:213], v[48:51]
	v_mfma_f32_16x16x32_bf16 v[44:47], v[136:139], v[210:213], v[44:47]
	v_mfma_f32_16x16x32_bf16 v[32:35], v[128:131], v[218:221], v[32:35]
	v_mfma_f32_16x16x32_bf16 v[28:31], v[136:139], v[218:221], v[28:31]
	v_mfma_f32_16x16x32_bf16 v[16:19], v[128:131], v[226:229], v[16:19]
	v_mfma_f32_16x16x32_bf16 v[12:15], v[136:139], v[226:229], v[12:15]
	v_mfma_f32_16x16x32_bf16 v[64:67], v[132:135], v[206:209], v[64:67]
	v_mfma_f32_16x16x32_bf16 v[60:63], v[144:147], v[206:209], v[60:63]
	v_mfma_f32_16x16x32_bf16 v[48:51], v[132:135], v[214:217], v[48:51]
	v_mfma_f32_16x16x32_bf16 v[44:47], v[144:147], v[214:217], v[44:47]
	v_mfma_f32_16x16x32_bf16 v[32:35], v[132:135], v[222:225], v[32:35]
	v_mfma_f32_16x16x32_bf16 v[28:31], v[144:147], v[222:225], v[28:31]
	v_mfma_f32_16x16x32_bf16 v[16:19], v[132:135], v[230:233], v[16:19]
	v_mfma_f32_16x16x32_bf16 v[12:15], v[144:147], v[230:233], v[12:15]
	v_mfma_f32_16x16x32_bf16 v[56:59], v[164:167], v[202:205], v[56:59]
	v_mfma_f32_16x16x32_bf16 v[52:55], v[194:197], v[202:205], v[52:55]
	v_mfma_f32_16x16x32_bf16 v[40:43], v[164:167], v[210:213], v[40:43]
	v_mfma_f32_16x16x32_bf16 v[36:39], v[194:197], v[210:213], v[36:39]
	v_mfma_f32_16x16x32_bf16 v[24:27], v[164:167], v[218:221], v[24:27]
	v_mfma_f32_16x16x32_bf16 v[20:23], v[194:197], v[218:221], v[20:23]
	v_mfma_f32_16x16x32_bf16 v[8:11], v[164:167], v[226:229], v[8:11]
	v_mfma_f32_16x16x32_bf16 v[4:7], v[194:197], v[226:229], v[4:7]
	v_mfma_f32_16x16x32_bf16 v[56:59], v[190:193], v[206:209], v[56:59]
	v_mfma_f32_16x16x32_bf16 v[52:55], v[198:201], v[206:209], v[52:55]
	v_mfma_f32_16x16x32_bf16 v[40:43], v[190:193], v[214:217], v[40:43]
	v_mfma_f32_16x16x32_bf16 v[36:39], v[198:201], v[214:217], v[36:39]
	v_mfma_f32_16x16x32_bf16 v[24:27], v[190:193], v[222:225], v[24:27]
	v_mfma_f32_16x16x32_bf16 v[20:23], v[198:201], v[222:225], v[20:23]
	v_mfma_f32_16x16x32_bf16 v[8:11], v[190:193], v[230:233], v[8:11]
	v_mfma_f32_16x16x32_bf16 v[4:7], v[198:201], v[230:233], v[4:7]
	s_add_u32 s15, s15, 0x100
	s_addc_u32 s23, s23, 0
	s_add_u32 s10, s10, 0x100
	s_addc_u32 s11, s11, 0
	s_cmp_ge_i32 s24, s17
	s_mov_b32 s12, s24
	s_barrier
	s_cbranch_scc0 .LBB0_676
	s_setprio 0
	s_and_b64 vcc, exec, s[46:47]
	s_cbranch_vccz .LBB0_679
	s_barrier

.Lsp_done_4:
.LBB0_766:
	s_add_u32 s10, vcc_lo, 0xfffc0080
	s_addc_u32 s11, vcc_hi, -1
	s_add_i32 s36, 0, 0x10000
	s_cmp_eq_u32 s77, 12
	s_cselect_b32 s13, s59, s11
	s_cselect_b32 s12, s74, s10
	v_add_u32_e32 v152, s36, v3
	s_cselect_b32 s11, s9, s27
	s_cselect_b32 s10, s23, s24
	s_add_i32 s0, 0, 0x14000
	ds_read_b128 v[168:171], v152
	ds_read_b128 v[172:175], v152 offset:1024
	ds_read_b128 v[190:193], v152 offset:2048
	ds_read_b128 v[194:197], v152 offset:3072
	v_add_u32_e32 v152, s0, v3
	ds_read_b128 v[198:201], v152
	ds_read_b128 v[202:205], v152 offset:1024
	ds_read_b128 v[206:209], v152 offset:2048
	ds_read_b128 v[210:213], v152 offset:3072
	v_lshl_add_u64 v[164:165], vcc, 0, v[162:163]
	s_add_i32 m0, s15, 0xc000
	ds_read_b128 v[214:217], v167
	ds_read_b128 v[218:221], v167 offset:1024
	ds_read_b128 v[222:225], v167 offset:2048
	ds_read_b128 v[226:229], v167 offset:3072
	ds_read_b128 v[230:233], v167 offset:4096
	ds_read_b128 v[234:237], v167 offset:5120
	ds_read_b128 v[238:241], v167 offset:6144
	ds_read_b128 v[242:245], v167 offset:7168
	global_load_lds_dwordx4 v[164:165], off
	v_lshl_add_u64 v[164:165], vcc, 0, v[160:161]
	s_add_i32 m0, s15, 0xe000
	s_nop 0
	global_load_lds_dwordx4 v[164:165], off
	s_waitcnt vmcnt(8)
	s_waitcnt lgkmcnt(0)
	s_barrier
	s_waitcnt lgkmcnt(0)
	v_mfma_f32_16x16x32_bf16 v[128:131], v[168:171], v[214:217], v[128:131]
	v_mfma_f32_16x16x32_bf16 v[124:127], v[190:193], v[214:217], v[124:127]
	v_mfma_f32_16x16x32_bf16 v[116:119], v[168:171], v[222:225], v[116:119]
	v_mfma_f32_16x16x32_bf16 v[108:111], v[190:193], v[222:225], v[108:111]
	v_mfma_f32_16x16x32_bf16 v[100:103], v[168:171], v[230:233], v[100:103]
	v_mfma_f32_16x16x32_bf16 v[92:95], v[190:193], v[230:233], v[92:95]
	v_mfma_f32_16x16x32_bf16 v[84:87], v[168:171], v[238:241], v[84:87]
	v_mfma_f32_16x16x32_bf16 v[76:79], v[190:193], v[238:241], v[76:79]
	v_mfma_f32_16x16x32_bf16 v[128:131], v[172:175], v[218:221], v[128:131]
	v_mfma_f32_16x16x32_bf16 v[124:127], v[194:197], v[218:221], v[124:127]
	v_mfma_f32_16x16x32_bf16 v[116:119], v[172:175], v[226:229], v[116:119]
	v_mfma_f32_16x16x32_bf16 v[108:111], v[194:197], v[226:229], v[108:111]
	v_mfma_f32_16x16x32_bf16 v[100:103], v[172:175], v[234:237], v[100:103]
	v_mfma_f32_16x16x32_bf16 v[92:95], v[194:197], v[234:237], v[92:95]
	v_mfma_f32_16x16x32_bf16 v[84:87], v[172:175], v[242:245], v[84:87]
	v_mfma_f32_16x16x32_bf16 v[76:79], v[194:197], v[242:245], v[76:79]
	v_mfma_f32_16x16x32_bf16 v[120:123], v[198:201], v[214:217], v[120:123]
	v_mfma_f32_16x16x32_bf16 v[112:115], v[206:209], v[214:217], v[112:115]
	v_mfma_f32_16x16x32_bf16 v[104:107], v[198:201], v[222:225], v[104:107]
	v_mfma_f32_16x16x32_bf16 v[96:99], v[206:209], v[222:225], v[96:99]
	v_mfma_f32_16x16x32_bf16 v[88:91], v[198:201], v[230:233], v[88:91]
	v_mfma_f32_16x16x32_bf16 v[80:83], v[206:209], v[230:233], v[80:83]
	v_mfma_f32_16x16x32_bf16 v[72:75], v[198:201], v[238:241], v[72:75]
	v_mfma_f32_16x16x32_bf16 v[68:71], v[206:209], v[238:241], v[68:71]
	v_mfma_f32_16x16x32_bf16 v[120:123], v[202:205], v[218:221], v[120:123]
	v_mfma_f32_16x16x32_bf16 v[112:115], v[210:213], v[218:221], v[112:115]
	v_mfma_f32_16x16x32_bf16 v[104:107], v[202:205], v[226:229], v[104:107]
	v_mfma_f32_16x16x32_bf16 v[96:99], v[210:213], v[226:229], v[96:99]
	v_mfma_f32_16x16x32_bf16 v[88:91], v[202:205], v[234:237], v[88:91]
	v_mfma_f32_16x16x32_bf16 v[80:83], v[210:213], v[234:237], v[80:83]
	v_mfma_f32_16x16x32_bf16 v[72:75], v[202:205], v[242:245], v[72:75]
	v_mfma_f32_16x16x32_bf16 v[68:71], v[210:213], v[242:245], v[68:71]
	s_barrier
	s_add_i32 s1, s36, s90
	v_lshl_add_u64 v[164:165], s[10:11], 0, v[0:1]
	s_mov_b32 m0, s1
	ds_read_b128 v[214:217], v167 offset:16384
	ds_read_b128 v[218:221], v167 offset:17408
	ds_read_b128 v[222:225], v167 offset:18432
	ds_read_b128 v[226:229], v167 offset:19456
	ds_read_b128 v[230:233], v167 offset:20480
	ds_read_b128 v[234:237], v167 offset:21504
	ds_read_b128 v[238:241], v167 offset:22528
	ds_read_b128 v[242:245], v167 offset:23552
	global_load_lds_dwordx4 v[164:165], off
	s_add_i32 m0, s1, 0x2000
	s_add_u32 s36, s10, 0x40000
	v_lshl_add_u64 v[246:247], s[10:11], 0, v[132:133]
	s_addc_u32 s37, s11, 0
	s_add_i32 s0, s0, s90
	global_load_lds_dwordx4 v[246:247], off
	v_lshl_add_u64 v[248:249], s[36:37], 0, v[0:1]
	s_mov_b32 m0, s0
	v_lshl_add_u64 v[250:251], s[12:13], 0, v[132:133]
	global_load_lds_dwordx4 v[248:249], off
	v_lshl_add_u64 v[248:249], s[36:37], 0, v[132:133]
	s_add_i32 m0, s0, 0x2000
	s_nop 0
	global_load_lds_dwordx4 v[248:249], off
	v_lshl_add_u64 v[248:249], s[12:13], 0, v[0:1]
	s_mov_b32 m0, s15
	s_nop 0
	global_load_lds_dwordx4 v[248:249], off
	s_mov_b32 m0, s91
	s_nop 0
	global_load_lds_dwordx4 v[250:251], off
	s_waitcnt vmcnt(8)
	s_waitcnt lgkmcnt(0)
	s_barrier
	s_waitcnt lgkmcnt(0)
	v_mfma_f32_16x16x32_bf16 v[64:67], v[168:171], v[214:217], v[64:67]
	v_mfma_f32_16x16x32_bf16 v[60:63], v[190:193], v[214:217], v[60:63]
	v_mfma_f32_16x16x32_bf16 v[52:55], v[168:171], v[222:225], v[52:55]
	v_mfma_f32_16x16x32_bf16 v[44:47], v[190:193], v[222:225], v[44:47]
	v_mfma_f32_16x16x32_bf16 v[36:39], v[168:171], v[230:233], v[36:39]
	v_mfma_f32_16x16x32_bf16 v[28:31], v[190:193], v[230:233], v[28:31]
	v_mfma_f32_16x16x32_bf16 v[20:23], v[168:171], v[238:241], v[20:23]
	v_mfma_f32_16x16x32_bf16 v[12:15], v[190:193], v[238:241], v[12:15]
	v_mfma_f32_16x16x32_bf16 v[64:67], v[172:175], v[218:221], v[64:67]
	v_mfma_f32_16x16x32_bf16 v[60:63], v[194:197], v[218:221], v[60:63]
	v_mfma_f32_16x16x32_bf16 v[52:55], v[172:175], v[226:229], v[52:55]
	v_mfma_f32_16x16x32_bf16 v[44:47], v[194:197], v[226:229], v[44:47]
	v_mfma_f32_16x16x32_bf16 v[36:39], v[172:175], v[234:237], v[36:39]
	v_mfma_f32_16x16x32_bf16 v[28:31], v[194:197], v[234:237], v[28:31]
	v_mfma_f32_16x16x32_bf16 v[20:23], v[172:175], v[242:245], v[20:23]
	v_mfma_f32_16x16x32_bf16 v[12:15], v[194:197], v[242:245], v[12:15]
	v_mfma_f32_16x16x32_bf16 v[56:59], v[198:201], v[214:217], v[56:59]
	v_mfma_f32_16x16x32_bf16 v[48:51], v[206:209], v[214:217], v[48:51]
	v_mfma_f32_16x16x32_bf16 v[40:43], v[198:201], v[222:225], v[40:43]
	v_mfma_f32_16x16x32_bf16 v[32:35], v[206:209], v[222:225], v[32:35]
	v_mfma_f32_16x16x32_bf16 v[24:27], v[198:201], v[230:233], v[24:27]
	v_mfma_f32_16x16x32_bf16 v[16:19], v[206:209], v[230:233], v[16:19]
	v_mfma_f32_16x16x32_bf16 v[8:11], v[198:201], v[238:241], v[8:11]
	v_mfma_f32_16x16x32_bf16 v[4:7], v[206:209], v[238:241], v[4:7]
	v_mfma_f32_16x16x32_bf16 v[56:59], v[202:205], v[218:221], v[56:59]
	v_mfma_f32_16x16x32_bf16 v[48:51], v[210:213], v[218:221], v[48:51]
	v_mfma_f32_16x16x32_bf16 v[40:43], v[202:205], v[226:229], v[40:43]
	v_mfma_f32_16x16x32_bf16 v[32:35], v[210:213], v[226:229], v[32:35]
	v_mfma_f32_16x16x32_bf16 v[24:27], v[202:205], v[234:237], v[24:27]
	v_mfma_f32_16x16x32_bf16 v[16:19], v[210:213], v[234:237], v[16:19]
	v_mfma_f32_16x16x32_bf16 v[8:11], v[202:205], v[242:245], v[8:11]
	v_mfma_f32_16x16x32_bf16 v[4:7], v[210:213], v[242:245], v[4:7]
	s_barrier
	s_add_i32 s0, 0, 0x18000
	v_add_u32_e32 v152, s0, v3
	s_add_i32 s1, 0, 0x1c000
	ds_read_b128 v[168:171], v152
	ds_read_b128 v[172:175], v152 offset:1024
	ds_read_b128 v[190:193], v152 offset:2048
	ds_read_b128 v[194:197], v152 offset:3072
	v_add_u32_e32 v152, s1, v3
	ds_read_b128 v[198:201], v152
	ds_read_b128 v[202:205], v152 offset:1024
	ds_read_b128 v[206:209], v152 offset:2048
	ds_read_b128 v[210:213], v152 offset:3072
	s_add_u32 s12, s12, 0x40000
	s_addc_u32 s13, s13, 0
	s_mov_b32 m0, s31
	v_lshl_add_u64 v[152:153], s[12:13], 0, v[0:1]
	ds_read_b128 v[214:217], v167 offset:32768
	ds_read_b128 v[218:221], v167 offset:33792
	ds_read_b128 v[222:225], v167 offset:34816
	ds_read_b128 v[226:229], v167 offset:35840
	ds_read_b128 v[230:233], v167 offset:36864
	ds_read_b128 v[234:237], v167 offset:37888
	ds_read_b128 v[238:241], v167 offset:38912
	ds_read_b128 v[242:245], v167 offset:39936
	global_load_lds_dwordx4 v[152:153], off
	v_lshl_add_u64 v[152:153], s[12:13], 0, v[132:133]
	s_mov_b32 m0, s22
	s_nop 0
	global_load_lds_dwordx4 v[152:153], off
	s_waitcnt vmcnt(8)
	s_waitcnt lgkmcnt(0)
	s_barrier
	s_waitcnt lgkmcnt(0)
	v_mfma_f32_16x16x32_bf16 v[128:131], v[168:171], v[214:217], v[128:131]
	v_mfma_f32_16x16x32_bf16 v[124:127], v[190:193], v[214:217], v[124:127]
	v_mfma_f32_16x16x32_bf16 v[116:119], v[168:171], v[222:225], v[116:119]
	v_mfma_f32_16x16x32_bf16 v[108:111], v[190:193], v[222:225], v[108:111]
	v_mfma_f32_16x16x32_bf16 v[100:103], v[168:171], v[230:233], v[100:103]
	v_mfma_f32_16x16x32_bf16 v[92:95], v[190:193], v[230:233], v[92:95]
	v_mfma_f32_16x16x32_bf16 v[84:87], v[168:171], v[238:241], v[84:87]
	v_mfma_f32_16x16x32_bf16 v[76:79], v[190:193], v[238:241], v[76:79]
	v_mfma_f32_16x16x32_bf16 v[128:131], v[172:175], v[218:221], v[128:131]
	v_mfma_f32_16x16x32_bf16 v[124:127], v[194:197], v[218:221], v[124:127]
	v_mfma_f32_16x16x32_bf16 v[116:119], v[172:175], v[226:229], v[116:119]
	v_mfma_f32_16x16x32_bf16 v[108:111], v[194:197], v[226:229], v[108:111]
	v_mfma_f32_16x16x32_bf16 v[100:103], v[172:175], v[234:237], v[100:103]
	v_mfma_f32_16x16x32_bf16 v[92:95], v[194:197], v[234:237], v[92:95]
	v_mfma_f32_16x16x32_bf16 v[84:87], v[172:175], v[242:245], v[84:87]
	v_mfma_f32_16x16x32_bf16 v[76:79], v[194:197], v[242:245], v[76:79]
	v_mfma_f32_16x16x32_bf16 v[120:123], v[198:201], v[214:217], v[120:123]
	v_mfma_f32_16x16x32_bf16 v[112:115], v[206:209], v[214:217], v[112:115]
	v_mfma_f32_16x16x32_bf16 v[104:107], v[198:201], v[222:225], v[104:107]
	v_mfma_f32_16x16x32_bf16 v[96:99], v[206:209], v[222:225], v[96:99]
	v_mfma_f32_16x16x32_bf16 v[88:91], v[198:201], v[230:233], v[88:91]
	v_mfma_f32_16x16x32_bf16 v[80:83], v[206:209], v[230:233], v[80:83]
	v_mfma_f32_16x16x32_bf16 v[72:75], v[198:201], v[238:241], v[72:75]
	v_mfma_f32_16x16x32_bf16 v[68:71], v[206:209], v[238:241], v[68:71]
	v_mfma_f32_16x16x32_bf16 v[120:123], v[202:205], v[218:221], v[120:123]
	v_mfma_f32_16x16x32_bf16 v[112:115], v[210:213], v[218:221], v[112:115]
	v_mfma_f32_16x16x32_bf16 v[104:107], v[202:205], v[226:229], v[104:107]
	v_mfma_f32_16x16x32_bf16 v[96:99], v[210:213], v[226:229], v[96:99]
	v_mfma_f32_16x16x32_bf16 v[88:91], v[202:205], v[234:237], v[88:91]
	v_mfma_f32_16x16x32_bf16 v[80:83], v[210:213], v[234:237], v[80:83]
	v_mfma_f32_16x16x32_bf16 v[72:75], v[202:205], v[242:245], v[72:75]
	v_mfma_f32_16x16x32_bf16 v[68:71], v[210:213], v[242:245], v[68:71]
	s_barrier
	s_add_i32 s0, s0, s90
	v_lshl_add_u64 v[152:153], v[164:165], 0, s[84:85]
	s_mov_b32 m0, s0
	ds_read_b128 v[214:217], v167 offset:49152
	ds_read_b128 v[218:221], v167 offset:50176
	ds_read_b128 v[222:225], v167 offset:51200
	ds_read_b128 v[226:229], v167 offset:52224
	ds_read_b128 v[230:233], v167 offset:53248
	ds_read_b128 v[234:237], v167 offset:54272
	ds_read_b128 v[238:241], v167 offset:55296
	ds_read_b128 v[242:245], v167 offset:56320
	global_load_lds_dwordx4 v[152:153], off
	s_add_i32 m0, s0, 0x2000
	s_add_u32 s10, s10, 0x40080
	v_lshl_add_u64 v[152:153], v[246:247], 0, s[84:85]
	s_addc_u32 s11, s11, 0
	s_add_i32 s0, s1, s90
	global_load_lds_dwordx4 v[152:153], off
	v_lshl_add_u64 v[152:153], s[10:11], 0, v[0:1]
	s_mov_b32 m0, s0
	s_nop 0
	global_load_lds_dwordx4 v[152:153], off
	v_lshl_add_u64 v[152:153], s[10:11], 0, v[132:133]
	s_add_i32 m0, s0, 0x2000
	s_nop 0
	global_load_lds_dwordx4 v[152:153], off
	v_lshl_add_u64 v[152:153], v[248:249], 0, s[84:85]
	s_mov_b32 m0, s94
	s_nop 0
	global_load_lds_dwordx4 v[152:153], off
	v_lshl_add_u64 v[152:153], v[250:251], 0, s[84:85]
	s_mov_b32 m0, s70
	s_nop 0
	global_load_lds_dwordx4 v[152:153], off
	s_waitcnt vmcnt(8)
	s_waitcnt lgkmcnt(0)
	s_barrier
	s_waitcnt lgkmcnt(0)
	v_mfma_f32_16x16x32_bf16 v[64:67], v[168:171], v[214:217], v[64:67]
	v_mfma_f32_16x16x32_bf16 v[60:63], v[190:193], v[214:217], v[60:63]
	v_mfma_f32_16x16x32_bf16 v[52:55], v[168:171], v[222:225], v[52:55]
	v_mfma_f32_16x16x32_bf16 v[44:47], v[190:193], v[222:225], v[44:47]
	v_mfma_f32_16x16x32_bf16 v[36:39], v[168:171], v[230:233], v[36:39]
	v_mfma_f32_16x16x32_bf16 v[28:31], v[190:193], v[230:233], v[28:31]
	v_mfma_f32_16x16x32_bf16 v[20:23], v[168:171], v[238:241], v[20:23]
	v_mfma_f32_16x16x32_bf16 v[12:15], v[190:193], v[238:241], v[12:15]
	v_mfma_f32_16x16x32_bf16 v[64:67], v[172:175], v[218:221], v[64:67]
	v_mfma_f32_16x16x32_bf16 v[60:63], v[194:197], v[218:221], v[60:63]
	v_mfma_f32_16x16x32_bf16 v[52:55], v[172:175], v[226:229], v[52:55]
	v_mfma_f32_16x16x32_bf16 v[44:47], v[194:197], v[226:229], v[44:47]
	v_mfma_f32_16x16x32_bf16 v[36:39], v[172:175], v[234:237], v[36:39]
	v_mfma_f32_16x16x32_bf16 v[28:31], v[194:197], v[234:237], v[28:31]
	v_mfma_f32_16x16x32_bf16 v[20:23], v[172:175], v[242:245], v[20:23]
	v_mfma_f32_16x16x32_bf16 v[12:15], v[194:197], v[242:245], v[12:15]
	v_mfma_f32_16x16x32_bf16 v[56:59], v[198:201], v[214:217], v[56:59]
	v_mfma_f32_16x16x32_bf16 v[48:51], v[206:209], v[214:217], v[48:51]
	v_mfma_f32_16x16x32_bf16 v[40:43], v[198:201], v[222:225], v[40:43]
	v_mfma_f32_16x16x32_bf16 v[32:35], v[206:209], v[222:225], v[32:35]
	v_mfma_f32_16x16x32_bf16 v[24:27], v[198:201], v[230:233], v[24:27]
	v_mfma_f32_16x16x32_bf16 v[16:19], v[206:209], v[230:233], v[16:19]
	v_mfma_f32_16x16x32_bf16 v[8:11], v[198:201], v[238:241], v[8:11]
	v_mfma_f32_16x16x32_bf16 v[4:7], v[206:209], v[238:241], v[4:7]
	v_mfma_f32_16x16x32_bf16 v[56:59], v[202:205], v[218:221], v[56:59]
	v_mfma_f32_16x16x32_bf16 v[48:51], v[210:213], v[218:221], v[48:51]
	v_mfma_f32_16x16x32_bf16 v[40:43], v[202:205], v[226:229], v[40:43]
	v_mfma_f32_16x16x32_bf16 v[32:35], v[210:213], v[226:229], v[32:35]
	v_mfma_f32_16x16x32_bf16 v[24:27], v[202:205], v[234:237], v[24:27]
	v_mfma_f32_16x16x32_bf16 v[16:19], v[210:213], v[234:237], v[16:19]
	v_mfma_f32_16x16x32_bf16 v[8:11], v[202:205], v[242:245], v[8:11]
	v_mfma_f32_16x16x32_bf16 v[4:7], v[210:213], v[242:245], v[4:7]
	s_add_i32 s77, s77, 2
	s_add_u32 s24, s24, 0x100
	s_addc_u32 s27, s27, 0
	s_add_u32 vcc_lo, vcc_lo, 0x100
	s_addc_u32 vcc_hi, vcc_hi, 0
	s_cmp_gt_u32 s77, 13
	s_barrier
	s_cbranch_scc0 .LBB0_766
	s_setprio 0
	s_and_b64 vcc, exec, s[6:7]
	s_cbranch_vccz .LBB0_777
	s_barrier
	v_lshl_or_b32 v164, s14, 8, v166
	v_ashrrev_i32_e32 v165, 31, v164
	v_lshlrev_b64 v[190:191], 2, v[164:165]
	v_lshl_add_u64 v[190:191], s[2:3], 0, v[190:191]
	global_load_dwordx4 v[192:195], v[190:191], off
	global_load_dwordx4 v[196:199], v[190:191], off offset:64
	global_load_dwordx4 v[200:203], v[190:191], off offset:512
	global_load_dwordx4 v[204:207], v[190:191], off offset:576
	s_waitcnt vmcnt(0)
	s_and_saveexec_b64 s[10:11], s[38:39]
	s_cbranch_execnz .LBB0_778
